# BR0-2 merge epilogue rewritten: stash and merged loads batched (on top of OUT/FF2 fast path)
# speedup vs baseline: 1.0032x; 1.0032x over previous
; DI float bf_lo(unsigned u) { return __uint_as_float(u << 16); }
; DI float bf_hi(unsigned u) { return __uint_as_float(u & 0xffff0000u); }
; #define PK8(v0, v1) ((u32x4){pk2((v0)[0], (v0)[1]), pk2((v0)[2], (v0)[3]), pk2((v1)[0], (v1)[1]), pk2((v1)[2], (v1)[3])})
;     DI void operator()(const f32x4 (&acc)[2][2][4][2], const Unit& u, int wr, int wc, int fr, int fq, int tid, LAS unsigned char* lds) const {
;     ...
;         case K_BR0: case K_BR1: case K_BR2: { EPI_CASE_BEGIN
;             const u32x4* st = (const u32x4*)(ws + WS_STASH + (size_t)blockIdx.x * 131072) + tid; bf16_t* dst = (bf16_t*)(ws + WS_MERGED);
;             const bool first = u.kind == K_BR0;
; #pragma unroll
;             for (int ai = 0; ai < 2; ++ai)
; #pragma unroll
;                 for (int m = 0; m < 4; ++m) { const int row = row0 + ai * 128 + m * 16;
; #pragma unroll
;                     for (int bj = 0; bj < 2; ++bj) { const u32x4 g = st[((ai * 4 + m) * 2 + bj) * 512];
;                         u32x4* d = (u32x4*)(dst + (size_t)row * 1024 + u.pn * 256 + lc0 + bj * 128);
;                         const f32x4 a0 = acc[ai][bj][m][0], a1 = acc[ai][bj][m][1];
;                         f32x4 r0 = {bf_lo(g.x) * a0[0], bf_hi(g.x) * a0[1], bf_lo(g.y) * a0[2], bf_hi(g.y) * a0[3]}, r1 = {bf_lo(g.z) * a1[0], bf_hi(g.z) * a1[1], bf_lo(g.w) * a1[2], bf_hi(g.w) * a1[3]};
;                         if (!first) { const u32x4 o = *d; r0[0] += bf_lo(o.x); r0[1] += bf_hi(o.x); r0[2] += bf_lo(o.y); r0[3] += bf_hi(o.y); r1[0] += bf_lo(o.z); r1[1] += bf_hi(o.z); r1[2] += bf_lo(o.w); r1[3] += bf_hi(o.w); }
;                         *d = PK8(r0, r1); } }
;         } break;
.LBB0_465:
	s_andn2_b64 vcc, exec, s[44:45]
	s_cbranch_vccnz .LBB0_502
	s_cmp_gt_i32 s55, 7
	s_mov_b64 s[42:43], -1
	s_cbranch_scc0 .LBB0_500
	s_waitcnt lgkmcnt(0)
	v_readlane_b32 s42, v254, 21
	v_readlane_b32 s43, v254, 22
	v_lshlrev_b32_e32 v166, 4, v231
	v_add_u32_e32 v167, s54, v230
	s_add_u32 s42, s50, s42
	s_addc_u32 s43, s51, s43
	s_add_u32 s42, s42, 0x17a00000
	s_addc_u32 s43, s43, 0
	v_lshl_add_u32 v0, v229, 3, s24
	s_lshl_b32 s2, s38, 9
	v_lshlrev_b32_e32 v167, 11, v167
	v_lshl_add_u32 v0, v0, 1, s2
	s_add_u32 s46, s50, 0x1aa00000
	s_addc_u32 s47, s51, 0
	v_add_u32_e32 v167, v167, v0
	s_cmp_eq_u32 s55, 8
	s_cbranch_scc1 .Lbr_first
	global_load_dwordx4 v[130:133], v166, s[42:43]
	global_load_dwordx4 v[204:207], v167, s[46:47]
	s_add_u32 s44, s42, 0x2000
	s_addc_u32 s45, s43, 0
	global_load_dwordx4 v[134:137], v166, s[44:45]
	global_load_dwordx4 v[236:239], v167, s[46:47] offset:256
	s_add_u32 s44, s42, 0x4000
	s_addc_u32 s45, s43, 0
	global_load_dwordx4 v[138:141], v166, s[44:45]
	s_add_u32 s44, s46, 0x8000
	s_addc_u32 s45, s47, 0
	global_load_dwordx4 v[240:243], v167, s[44:45]
	s_add_u32 s44, s42, 0x6000
	s_addc_u32 s45, s43, 0
	global_load_dwordx4 v[142:145], v166, s[44:45]
	s_add_u32 s44, s46, 0x8000
	s_addc_u32 s45, s47, 0
	global_load_dwordx4 v[244:247], v167, s[44:45] offset:256
	s_add_u32 s44, s42, 0x8000
	s_addc_u32 s45, s43, 0
	global_load_dwordx4 v[146:149], v166, s[44:45]
	s_add_u32 s44, s42, 0xa000
	s_addc_u32 s45, s43, 0
	global_load_dwordx4 v[150:153], v166, s[44:45]
	s_add_u32 s44, s42, 0xc000
	s_addc_u32 s45, s43, 0
	global_load_dwordx4 v[154:157], v166, s[44:45]
	s_add_u32 s44, s42, 0xe000
	s_addc_u32 s45, s43, 0
	global_load_dwordx4 v[158:161], v166, s[44:45]
	s_add_u32 s44, s42, 0x10000
	s_addc_u32 s45, s43, 0
	global_load_dwordx4 v[162:165], v166, s[44:45]
	s_add_u32 s44, s42, 0x12000
	s_addc_u32 s45, s43, 0
	global_load_dwordx4 v[176:179], v166, s[44:45]
	s_add_u32 s44, s42, 0x14000
	s_addc_u32 s45, s43, 0
	global_load_dwordx4 v[180:183], v166, s[44:45]
	s_add_u32 s44, s42, 0x16000
	s_addc_u32 s45, s43, 0
	global_load_dwordx4 v[184:187], v166, s[44:45]
	s_add_u32 s44, s42, 0x18000
	s_addc_u32 s45, s43, 0
	global_load_dwordx4 v[188:191], v166, s[44:45]
	s_add_u32 s44, s42, 0x1a000
	s_addc_u32 s45, s43, 0
	global_load_dwordx4 v[192:195], v166, s[44:45]
	s_add_u32 s44, s42, 0x1c000
	s_addc_u32 s45, s43, 0
	global_load_dwordx4 v[196:199], v166, s[44:45]
	s_add_u32 s44, s42, 0x1e000
	s_addc_u32 s45, s43, 0
	global_load_dwordx4 v[200:203], v166, s[44:45]
	s_waitcnt vmcnt(18)
	v_lshlrev_b32_e32 v248, 16, v130
	v_and_b32_e32 v249, 0xffff0000, v130
	v_pk_mul_f32 v[126:127], v[126:127], v[248:249]
	v_lshlrev_b32_e32 v250, 16, v131
	v_and_b32_e32 v251, 0xffff0000, v131
	v_pk_mul_f32 v[128:129], v[128:129], v[250:251]
	v_lshlrev_b32_e32 v248, 16, v132
	v_and_b32_e32 v249, 0xffff0000, v132
	v_pk_mul_f32 v[122:123], v[122:123], v[248:249]
	v_lshlrev_b32_e32 v250, 16, v133
	v_and_b32_e32 v251, 0xffff0000, v133
	v_pk_mul_f32 v[124:125], v[124:125], v[250:251]
	v_lshlrev_b32_e32 v248, 16, v204
	v_and_b32_e32 v249, 0xffff0000, v204
	v_pk_add_f32 v[126:127], v[126:127], v[248:249]
	v_lshlrev_b32_e32 v250, 16, v205
	v_and_b32_e32 v251, 0xffff0000, v205
	v_pk_add_f32 v[128:129], v[128:129], v[250:251]
	v_lshlrev_b32_e32 v248, 16, v206
	v_and_b32_e32 v249, 0xffff0000, v206
	v_pk_add_f32 v[122:123], v[122:123], v[248:249]
	v_lshlrev_b32_e32 v250, 16, v207
	v_and_b32_e32 v251, 0xffff0000, v207
	v_pk_add_f32 v[124:125], v[124:125], v[250:251]
	v_cvt_pk_bf16_f32 v204, v126, v127
	v_cvt_pk_bf16_f32 v205, v128, v129
	v_cvt_pk_bf16_f32 v206, v122, v123
	v_cvt_pk_bf16_f32 v207, v124, v125
	global_store_dwordx4 v167, v[204:207], s[46:47]
	s_add_u32 s44, s46, 0x10000
	s_addc_u32 s45, s47, 0
	global_load_dwordx4 v[130:133], v167, s[44:45]
	s_waitcnt vmcnt(18)
	v_lshlrev_b32_e32 v248, 16, v134
	v_and_b32_e32 v249, 0xffff0000, v134
	v_pk_mul_f32 v[118:119], v[118:119], v[248:249]
	v_lshlrev_b32_e32 v250, 16, v135
	v_and_b32_e32 v251, 0xffff0000, v135
	v_pk_mul_f32 v[120:121], v[120:121], v[250:251]
	v_lshlrev_b32_e32 v248, 16, v136
	v_and_b32_e32 v249, 0xffff0000, v136
	v_pk_mul_f32 v[114:115], v[114:115], v[248:249]
	v_lshlrev_b32_e32 v250, 16, v137
	v_and_b32_e32 v251, 0xffff0000, v137
	v_pk_mul_f32 v[116:117], v[116:117], v[250:251]
	v_lshlrev_b32_e32 v248, 16, v236
	v_and_b32_e32 v249, 0xffff0000, v236
	v_pk_add_f32 v[118:119], v[118:119], v[248:249]
	v_lshlrev_b32_e32 v250, 16, v237
	v_and_b32_e32 v251, 0xffff0000, v237
	v_pk_add_f32 v[120:121], v[120:121], v[250:251]
	v_lshlrev_b32_e32 v248, 16, v238
	v_and_b32_e32 v249, 0xffff0000, v238
	v_pk_add_f32 v[114:115], v[114:115], v[248:249]
	v_lshlrev_b32_e32 v250, 16, v239
	v_and_b32_e32 v251, 0xffff0000, v239
	v_pk_add_f32 v[116:117], v[116:117], v[250:251]
	v_cvt_pk_bf16_f32 v236, v118, v119
	v_cvt_pk_bf16_f32 v237, v120, v121
	v_cvt_pk_bf16_f32 v238, v114, v115
	v_cvt_pk_bf16_f32 v239, v116, v117
	global_store_dwordx4 v167, v[236:239], s[46:47] offset:256
	s_add_u32 s44, s46, 0x10000
	s_addc_u32 s45, s47, 0
	global_load_dwordx4 v[134:137], v167, s[44:45] offset:256
	s_waitcnt vmcnt(18)
; DI float bf_lo(unsigned u) { return __uint_as_float(u << 16); }
; DI float bf_hi(unsigned u) { return __uint_as_float(u & 0xffff0000u); }
; #define PK8(v0, v1) ((u32x4){pk2((v0)[0], (v0)[1]), pk2((v0)[2], (v0)[3]), pk2((v1)[0], (v1)[1]), pk2((v1)[2], (v1)[3])})
;     DI void operator()(const f32x4 (&acc)[2][2][4][2], const Unit& u, int wr, int wc, int fr, int fq, int tid, LAS unsigned char* lds) const {
;     ...
;             for (int ai = 0; ai < 2; ++ai)
; #pragma unroll
;                 for (int m = 0; m < 4; ++m) { const int row = row0 + ai * 128 + m * 16;
; #pragma unroll
;                     for (int bj = 0; bj < 2; ++bj) { const u32x4 g = st[((ai * 4 + m) * 2 + bj) * 512];
;                         u32x4* d = (u32x4*)(dst + (size_t)row * 1024 + u.pn * 256 + lc0 + bj * 128);
;                         const f32x4 a0 = acc[ai][bj][m][0], a1 = acc[ai][bj][m][1];
;                         f32x4 r0 = {bf_lo(g.x) * a0[0], bf_hi(g.x) * a0[1], bf_lo(g.y) * a0[2], bf_hi(g.y) * a0[3]}, r1 = {bf_lo(g.z) * a1[0], bf_hi(g.z) * a1[1], bf_lo(g.w) * a1[2], bf_hi(g.w) * a1[3]};
;                         if (!first) { const u32x4 o = *d; r0[0] += bf_lo(o.x); r0[1] += bf_hi(o.x); r0[2] += bf_lo(o.y); r0[3] += bf_hi(o.y); r1[0] += bf_lo(o.z); r1[1] += bf_hi(o.z); r1[2] += bf_lo(o.w); r1[3] += bf_hi(o.w); }
;                         *d = PK8(r0, r1); } }
	v_lshlrev_b32_e32 v248, 16, v138
	v_and_b32_e32 v249, 0xffff0000, v138
	v_pk_mul_f32 v[110:111], v[110:111], v[248:249]
	v_lshlrev_b32_e32 v250, 16, v139
	v_and_b32_e32 v251, 0xffff0000, v139
	v_pk_mul_f32 v[112:113], v[112:113], v[250:251]
	v_lshlrev_b32_e32 v248, 16, v140
	v_and_b32_e32 v249, 0xffff0000, v140
	v_pk_mul_f32 v[106:107], v[106:107], v[248:249]
	v_lshlrev_b32_e32 v250, 16, v141
	v_and_b32_e32 v251, 0xffff0000, v141
	v_pk_mul_f32 v[108:109], v[108:109], v[250:251]
	v_lshlrev_b32_e32 v248, 16, v240
	v_and_b32_e32 v249, 0xffff0000, v240
	v_pk_add_f32 v[110:111], v[110:111], v[248:249]
	v_lshlrev_b32_e32 v250, 16, v241
	v_and_b32_e32 v251, 0xffff0000, v241
	v_pk_add_f32 v[112:113], v[112:113], v[250:251]
	v_lshlrev_b32_e32 v248, 16, v242
	v_and_b32_e32 v249, 0xffff0000, v242
	v_pk_add_f32 v[106:107], v[106:107], v[248:249]
	v_lshlrev_b32_e32 v250, 16, v243
	v_and_b32_e32 v251, 0xffff0000, v243
	v_pk_add_f32 v[108:109], v[108:109], v[250:251]
	v_cvt_pk_bf16_f32 v240, v110, v111
	v_cvt_pk_bf16_f32 v241, v112, v113
	v_cvt_pk_bf16_f32 v242, v106, v107
	v_cvt_pk_bf16_f32 v243, v108, v109
	s_add_u32 s44, s46, 0x8000
	s_addc_u32 s45, s47, 0
	global_store_dwordx4 v167, v[240:243], s[44:45]
	s_add_u32 s44, s46, 0x18000
	s_addc_u32 s45, s47, 0
	global_load_dwordx4 v[138:141], v167, s[44:45]
	s_waitcnt vmcnt(18)
	v_lshlrev_b32_e32 v248, 16, v142
	v_and_b32_e32 v249, 0xffff0000, v142
	v_pk_mul_f32 v[102:103], v[102:103], v[248:249]
	v_lshlrev_b32_e32 v250, 16, v143
	v_and_b32_e32 v251, 0xffff0000, v143
	v_pk_mul_f32 v[104:105], v[104:105], v[250:251]
	v_lshlrev_b32_e32 v248, 16, v144
	v_and_b32_e32 v249, 0xffff0000, v144
	v_pk_mul_f32 v[98:99], v[98:99], v[248:249]
	v_lshlrev_b32_e32 v250, 16, v145
	v_and_b32_e32 v251, 0xffff0000, v145
	v_pk_mul_f32 v[100:101], v[100:101], v[250:251]
	v_lshlrev_b32_e32 v248, 16, v244
	v_and_b32_e32 v249, 0xffff0000, v244
	v_pk_add_f32 v[102:103], v[102:103], v[248:249]
	v_lshlrev_b32_e32 v250, 16, v245
	v_and_b32_e32 v251, 0xffff0000, v245
	v_pk_add_f32 v[104:105], v[104:105], v[250:251]
	v_lshlrev_b32_e32 v248, 16, v246
	v_and_b32_e32 v249, 0xffff0000, v246
	v_pk_add_f32 v[98:99], v[98:99], v[248:249]
	v_lshlrev_b32_e32 v250, 16, v247
	v_and_b32_e32 v251, 0xffff0000, v247
	v_pk_add_f32 v[100:101], v[100:101], v[250:251]
	v_cvt_pk_bf16_f32 v244, v102, v103
	v_cvt_pk_bf16_f32 v245, v104, v105
	v_cvt_pk_bf16_f32 v246, v98, v99
	v_cvt_pk_bf16_f32 v247, v100, v101
	s_add_u32 s44, s46, 0x8000
	s_addc_u32 s45, s47, 0
	global_store_dwordx4 v167, v[244:247], s[44:45] offset:256
	s_add_u32 s44, s46, 0x18000
	s_addc_u32 s45, s47, 0
	global_load_dwordx4 v[142:145], v167, s[44:45] offset:256
	s_waitcnt vmcnt(6)
	v_lshlrev_b32_e32 v248, 16, v146
	v_and_b32_e32 v249, 0xffff0000, v146
	v_pk_mul_f32 v[94:95], v[94:95], v[248:249]
	v_lshlrev_b32_e32 v250, 16, v147
	v_and_b32_e32 v251, 0xffff0000, v147
	v_pk_mul_f32 v[96:97], v[96:97], v[250:251]
	v_lshlrev_b32_e32 v248, 16, v148
	v_and_b32_e32 v249, 0xffff0000, v148
	v_pk_mul_f32 v[90:91], v[90:91], v[248:249]
	v_lshlrev_b32_e32 v250, 16, v149
	v_and_b32_e32 v251, 0xffff0000, v149
	v_pk_mul_f32 v[92:93], v[92:93], v[250:251]
	v_lshlrev_b32_e32 v248, 16, v130
	v_and_b32_e32 v249, 0xffff0000, v130
	v_pk_add_f32 v[94:95], v[94:95], v[248:249]
	v_lshlrev_b32_e32 v250, 16, v131
	v_and_b32_e32 v251, 0xffff0000, v131
	v_pk_add_f32 v[96:97], v[96:97], v[250:251]
	v_lshlrev_b32_e32 v248, 16, v132
	v_and_b32_e32 v249, 0xffff0000, v132
	v_pk_add_f32 v[90:91], v[90:91], v[248:249]
	v_lshlrev_b32_e32 v250, 16, v133
	v_and_b32_e32 v251, 0xffff0000, v133
	v_pk_add_f32 v[92:93], v[92:93], v[250:251]
	v_cvt_pk_bf16_f32 v130, v94, v95
	v_cvt_pk_bf16_f32 v131, v96, v97
	v_cvt_pk_bf16_f32 v132, v90, v91
	v_cvt_pk_bf16_f32 v133, v92, v93
	s_add_u32 s44, s46, 0x10000
	s_addc_u32 s45, s47, 0
	global_store_dwordx4 v167, v[130:133], s[44:45]
	s_add_u32 s44, s46, 0x40000
	s_addc_u32 s45, s47, 0
	global_load_dwordx4 v[146:149], v167, s[44:45]
	s_waitcnt vmcnt(6)
	v_lshlrev_b32_e32 v248, 16, v150
	v_and_b32_e32 v249, 0xffff0000, v150
	v_pk_mul_f32 v[86:87], v[86:87], v[248:249]
	v_lshlrev_b32_e32 v250, 16, v151
	v_and_b32_e32 v251, 0xffff0000, v151
	v_pk_mul_f32 v[88:89], v[88:89], v[250:251]
	v_lshlrev_b32_e32 v248, 16, v152
	v_and_b32_e32 v249, 0xffff0000, v152
	v_pk_mul_f32 v[82:83], v[82:83], v[248:249]
	v_lshlrev_b32_e32 v250, 16, v153
	v_and_b32_e32 v251, 0xffff0000, v153
	v_pk_mul_f32 v[84:85], v[84:85], v[250:251]
	v_lshlrev_b32_e32 v248, 16, v134
	v_and_b32_e32 v249, 0xffff0000, v134
	v_pk_add_f32 v[86:87], v[86:87], v[248:249]
	v_lshlrev_b32_e32 v250, 16, v135
	v_and_b32_e32 v251, 0xffff0000, v135
	v_pk_add_f32 v[88:89], v[88:89], v[250:251]
	v_lshlrev_b32_e32 v248, 16, v136
	v_and_b32_e32 v249, 0xffff0000, v136
	v_pk_add_f32 v[82:83], v[82:83], v[248:249]
	v_lshlrev_b32_e32 v250, 16, v137
	v_and_b32_e32 v251, 0xffff0000, v137
	v_pk_add_f32 v[84:85], v[84:85], v[250:251]
	v_cvt_pk_bf16_f32 v134, v86, v87
	v_cvt_pk_bf16_f32 v135, v88, v89
	v_cvt_pk_bf16_f32 v136, v82, v83
	v_cvt_pk_bf16_f32 v137, v84, v85
	s_add_u32 s44, s46, 0x10000
	s_addc_u32 s45, s47, 0
	global_store_dwordx4 v167, v[134:137], s[44:45] offset:256
	s_add_u32 s44, s46, 0x40000
	s_addc_u32 s45, s47, 0
	global_load_dwordx4 v[150:153], v167, s[44:45] offset:256
	s_waitcnt vmcnt(6)
; DI float bf_lo(unsigned u) { return __uint_as_float(u << 16); }
; DI float bf_hi(unsigned u) { return __uint_as_float(u & 0xffff0000u); }
; #define PK8(v0, v1) ((u32x4){pk2((v0)[0], (v0)[1]), pk2((v0)[2], (v0)[3]), pk2((v1)[0], (v1)[1]), pk2((v1)[2], (v1)[3])})
;     DI void operator()(const f32x4 (&acc)[2][2][4][2], const Unit& u, int wr, int wc, int fr, int fq, int tid, LAS unsigned char* lds) const {
;     ...
;             for (int ai = 0; ai < 2; ++ai)
; #pragma unroll
;                 for (int m = 0; m < 4; ++m) { const int row = row0 + ai * 128 + m * 16;
; #pragma unroll
;                     for (int bj = 0; bj < 2; ++bj) { const u32x4 g = st[((ai * 4 + m) * 2 + bj) * 512];
;                         u32x4* d = (u32x4*)(dst + (size_t)row * 1024 + u.pn * 256 + lc0 + bj * 128);
;                         const f32x4 a0 = acc[ai][bj][m][0], a1 = acc[ai][bj][m][1];
;                         f32x4 r0 = {bf_lo(g.x) * a0[0], bf_hi(g.x) * a0[1], bf_lo(g.y) * a0[2], bf_hi(g.y) * a0[3]}, r1 = {bf_lo(g.z) * a1[0], bf_hi(g.z) * a1[1], bf_lo(g.w) * a1[2], bf_hi(g.w) * a1[3]};
;                         if (!first) { const u32x4 o = *d; r0[0] += bf_lo(o.x); r0[1] += bf_hi(o.x); r0[2] += bf_lo(o.y); r0[3] += bf_hi(o.y); r1[0] += bf_lo(o.z); r1[1] += bf_hi(o.z); r1[2] += bf_lo(o.w); r1[3] += bf_hi(o.w); }
;                         *d = PK8(r0, r1); } }
	v_lshlrev_b32_e32 v248, 16, v154
	v_and_b32_e32 v249, 0xffff0000, v154
	v_pk_mul_f32 v[78:79], v[78:79], v[248:249]
	v_lshlrev_b32_e32 v250, 16, v155
	v_and_b32_e32 v251, 0xffff0000, v155
	v_pk_mul_f32 v[80:81], v[80:81], v[250:251]
	v_lshlrev_b32_e32 v248, 16, v156
	v_and_b32_e32 v249, 0xffff0000, v156
	v_pk_mul_f32 v[74:75], v[74:75], v[248:249]
	v_lshlrev_b32_e32 v250, 16, v157
	v_and_b32_e32 v251, 0xffff0000, v157
	v_pk_mul_f32 v[76:77], v[76:77], v[250:251]
	v_lshlrev_b32_e32 v248, 16, v138
	v_and_b32_e32 v249, 0xffff0000, v138
	v_pk_add_f32 v[78:79], v[78:79], v[248:249]
	v_lshlrev_b32_e32 v250, 16, v139
	v_and_b32_e32 v251, 0xffff0000, v139
	v_pk_add_f32 v[80:81], v[80:81], v[250:251]
	v_lshlrev_b32_e32 v248, 16, v140
	v_and_b32_e32 v249, 0xffff0000, v140
	v_pk_add_f32 v[74:75], v[74:75], v[248:249]
	v_lshlrev_b32_e32 v250, 16, v141
	v_and_b32_e32 v251, 0xffff0000, v141
	v_pk_add_f32 v[76:77], v[76:77], v[250:251]
	v_cvt_pk_bf16_f32 v138, v78, v79
	v_cvt_pk_bf16_f32 v139, v80, v81
	v_cvt_pk_bf16_f32 v140, v74, v75
	v_cvt_pk_bf16_f32 v141, v76, v77
	s_add_u32 s44, s46, 0x18000
	s_addc_u32 s45, s47, 0
	global_store_dwordx4 v167, v[138:141], s[44:45]
	s_add_u32 s44, s46, 0x48000
	s_addc_u32 s45, s47, 0
	global_load_dwordx4 v[154:157], v167, s[44:45]
	s_waitcnt vmcnt(6)
	v_lshlrev_b32_e32 v248, 16, v158
	v_and_b32_e32 v249, 0xffff0000, v158
	v_pk_mul_f32 v[70:71], v[70:71], v[248:249]
	v_lshlrev_b32_e32 v250, 16, v159
	v_and_b32_e32 v251, 0xffff0000, v159
	v_pk_mul_f32 v[72:73], v[72:73], v[250:251]
	v_lshlrev_b32_e32 v248, 16, v160
	v_and_b32_e32 v249, 0xffff0000, v160
	v_pk_mul_f32 v[66:67], v[66:67], v[248:249]
	v_lshlrev_b32_e32 v250, 16, v161
	v_and_b32_e32 v251, 0xffff0000, v161
	v_pk_mul_f32 v[68:69], v[68:69], v[250:251]
	v_lshlrev_b32_e32 v248, 16, v142
	v_and_b32_e32 v249, 0xffff0000, v142
	v_pk_add_f32 v[70:71], v[70:71], v[248:249]
	v_lshlrev_b32_e32 v250, 16, v143
	v_and_b32_e32 v251, 0xffff0000, v143
	v_pk_add_f32 v[72:73], v[72:73], v[250:251]
	v_lshlrev_b32_e32 v248, 16, v144
	v_and_b32_e32 v249, 0xffff0000, v144
	v_pk_add_f32 v[66:67], v[66:67], v[248:249]
	v_lshlrev_b32_e32 v250, 16, v145
	v_and_b32_e32 v251, 0xffff0000, v145
	v_pk_add_f32 v[68:69], v[68:69], v[250:251]
	v_cvt_pk_bf16_f32 v142, v70, v71
	v_cvt_pk_bf16_f32 v143, v72, v73
	v_cvt_pk_bf16_f32 v144, v66, v67
	v_cvt_pk_bf16_f32 v145, v68, v69
	s_add_u32 s44, s46, 0x18000
	s_addc_u32 s45, s47, 0
	global_store_dwordx4 v167, v[142:145], s[44:45] offset:256
	s_add_u32 s44, s46, 0x48000
	s_addc_u32 s45, s47, 0
	global_load_dwordx4 v[158:161], v167, s[44:45] offset:256
	s_waitcnt vmcnt(6)
	v_lshlrev_b32_e32 v248, 16, v162
	v_and_b32_e32 v249, 0xffff0000, v162
	v_pk_mul_f32 v[62:63], v[62:63], v[248:249]
	v_lshlrev_b32_e32 v250, 16, v163
	v_and_b32_e32 v251, 0xffff0000, v163
	v_pk_mul_f32 v[64:65], v[64:65], v[250:251]
	v_lshlrev_b32_e32 v248, 16, v164
	v_and_b32_e32 v249, 0xffff0000, v164
	v_pk_mul_f32 v[58:59], v[58:59], v[248:249]
	v_lshlrev_b32_e32 v250, 16, v165
	v_and_b32_e32 v251, 0xffff0000, v165
	v_pk_mul_f32 v[60:61], v[60:61], v[250:251]
	v_lshlrev_b32_e32 v248, 16, v146
	v_and_b32_e32 v249, 0xffff0000, v146
	v_pk_add_f32 v[62:63], v[62:63], v[248:249]
	v_lshlrev_b32_e32 v250, 16, v147
	v_and_b32_e32 v251, 0xffff0000, v147
	v_pk_add_f32 v[64:65], v[64:65], v[250:251]
	v_lshlrev_b32_e32 v248, 16, v148
	v_and_b32_e32 v249, 0xffff0000, v148
	v_pk_add_f32 v[58:59], v[58:59], v[248:249]
	v_lshlrev_b32_e32 v250, 16, v149
	v_and_b32_e32 v251, 0xffff0000, v149
	v_pk_add_f32 v[60:61], v[60:61], v[250:251]
	v_cvt_pk_bf16_f32 v146, v62, v63
	v_cvt_pk_bf16_f32 v147, v64, v65
	v_cvt_pk_bf16_f32 v148, v58, v59
	v_cvt_pk_bf16_f32 v149, v60, v61
	s_add_u32 s44, s46, 0x40000
	s_addc_u32 s45, s47, 0
	global_store_dwordx4 v167, v[146:149], s[44:45]
	s_add_u32 s44, s46, 0x50000
	s_addc_u32 s45, s47, 0
	global_load_dwordx4 v[162:165], v167, s[44:45]
	s_waitcnt vmcnt(6)
	v_lshlrev_b32_e32 v248, 16, v176
	v_and_b32_e32 v249, 0xffff0000, v176
	v_pk_mul_f32 v[54:55], v[54:55], v[248:249]
	v_lshlrev_b32_e32 v250, 16, v177
	v_and_b32_e32 v251, 0xffff0000, v177
	v_pk_mul_f32 v[56:57], v[56:57], v[250:251]
	v_lshlrev_b32_e32 v248, 16, v178
	v_and_b32_e32 v249, 0xffff0000, v178
	v_pk_mul_f32 v[50:51], v[50:51], v[248:249]
	v_lshlrev_b32_e32 v250, 16, v179
	v_and_b32_e32 v251, 0xffff0000, v179
	v_pk_mul_f32 v[52:53], v[52:53], v[250:251]
	v_lshlrev_b32_e32 v248, 16, v150
	v_and_b32_e32 v249, 0xffff0000, v150
	v_pk_add_f32 v[54:55], v[54:55], v[248:249]
	v_lshlrev_b32_e32 v250, 16, v151
	v_and_b32_e32 v251, 0xffff0000, v151
	v_pk_add_f32 v[56:57], v[56:57], v[250:251]
	v_lshlrev_b32_e32 v248, 16, v152
	v_and_b32_e32 v249, 0xffff0000, v152
	v_pk_add_f32 v[50:51], v[50:51], v[248:249]
	v_lshlrev_b32_e32 v250, 16, v153
	v_and_b32_e32 v251, 0xffff0000, v153
	v_pk_add_f32 v[52:53], v[52:53], v[250:251]
	v_cvt_pk_bf16_f32 v150, v54, v55
	v_cvt_pk_bf16_f32 v151, v56, v57
	v_cvt_pk_bf16_f32 v152, v50, v51
	v_cvt_pk_bf16_f32 v153, v52, v53
	s_add_u32 s44, s46, 0x40000
	s_addc_u32 s45, s47, 0
	global_store_dwordx4 v167, v[150:153], s[44:45] offset:256
	s_add_u32 s44, s46, 0x50000
	s_addc_u32 s45, s47, 0
	global_load_dwordx4 v[176:179], v167, s[44:45] offset:256
	s_waitcnt vmcnt(6)
; DI float bf_lo(unsigned u) { return __uint_as_float(u << 16); }
; DI float bf_hi(unsigned u) { return __uint_as_float(u & 0xffff0000u); }
; #define PK8(v0, v1) ((u32x4){pk2((v0)[0], (v0)[1]), pk2((v0)[2], (v0)[3]), pk2((v1)[0], (v1)[1]), pk2((v1)[2], (v1)[3])})
;     DI void operator()(const f32x4 (&acc)[2][2][4][2], const Unit& u, int wr, int wc, int fr, int fq, int tid, LAS unsigned char* lds) const {
;     ...
;             for (int ai = 0; ai < 2; ++ai)
; #pragma unroll
;                 for (int m = 0; m < 4; ++m) { const int row = row0 + ai * 128 + m * 16;
; #pragma unroll
;                     for (int bj = 0; bj < 2; ++bj) { const u32x4 g = st[((ai * 4 + m) * 2 + bj) * 512];
;                         u32x4* d = (u32x4*)(dst + (size_t)row * 1024 + u.pn * 256 + lc0 + bj * 128);
;                         const f32x4 a0 = acc[ai][bj][m][0], a1 = acc[ai][bj][m][1];
;                         f32x4 r0 = {bf_lo(g.x) * a0[0], bf_hi(g.x) * a0[1], bf_lo(g.y) * a0[2], bf_hi(g.y) * a0[3]}, r1 = {bf_lo(g.z) * a1[0], bf_hi(g.z) * a1[1], bf_lo(g.w) * a1[2], bf_hi(g.w) * a1[3]};
;                         if (!first) { const u32x4 o = *d; r0[0] += bf_lo(o.x); r0[1] += bf_hi(o.x); r0[2] += bf_lo(o.y); r0[3] += bf_hi(o.y); r1[0] += bf_lo(o.z); r1[1] += bf_hi(o.z); r1[2] += bf_lo(o.w); r1[3] += bf_hi(o.w); }
;                         *d = PK8(r0, r1); } }
	v_lshlrev_b32_e32 v248, 16, v180
	v_and_b32_e32 v249, 0xffff0000, v180
	v_pk_mul_f32 v[46:47], v[46:47], v[248:249]
	v_lshlrev_b32_e32 v250, 16, v181
	v_and_b32_e32 v251, 0xffff0000, v181
	v_pk_mul_f32 v[48:49], v[48:49], v[250:251]
	v_lshlrev_b32_e32 v248, 16, v182
	v_and_b32_e32 v249, 0xffff0000, v182
	v_pk_mul_f32 v[42:43], v[42:43], v[248:249]
	v_lshlrev_b32_e32 v250, 16, v183
	v_and_b32_e32 v251, 0xffff0000, v183
	v_pk_mul_f32 v[44:45], v[44:45], v[250:251]
	v_lshlrev_b32_e32 v248, 16, v154
	v_and_b32_e32 v249, 0xffff0000, v154
	v_pk_add_f32 v[46:47], v[46:47], v[248:249]
	v_lshlrev_b32_e32 v250, 16, v155
	v_and_b32_e32 v251, 0xffff0000, v155
	v_pk_add_f32 v[48:49], v[48:49], v[250:251]
	v_lshlrev_b32_e32 v248, 16, v156
	v_and_b32_e32 v249, 0xffff0000, v156
	v_pk_add_f32 v[42:43], v[42:43], v[248:249]
	v_lshlrev_b32_e32 v250, 16, v157
	v_and_b32_e32 v251, 0xffff0000, v157
	v_pk_add_f32 v[44:45], v[44:45], v[250:251]
	v_cvt_pk_bf16_f32 v154, v46, v47
	v_cvt_pk_bf16_f32 v155, v48, v49
	v_cvt_pk_bf16_f32 v156, v42, v43
	v_cvt_pk_bf16_f32 v157, v44, v45
	s_add_u32 s44, s46, 0x48000
	s_addc_u32 s45, s47, 0
	global_store_dwordx4 v167, v[154:157], s[44:45]
	s_add_u32 s44, s46, 0x58000
	s_addc_u32 s45, s47, 0
	global_load_dwordx4 v[180:183], v167, s[44:45]
	s_waitcnt vmcnt(6)
	v_lshlrev_b32_e32 v248, 16, v184
	v_and_b32_e32 v249, 0xffff0000, v184
	v_pk_mul_f32 v[38:39], v[38:39], v[248:249]
	v_lshlrev_b32_e32 v250, 16, v185
	v_and_b32_e32 v251, 0xffff0000, v185
	v_pk_mul_f32 v[40:41], v[40:41], v[250:251]
	v_lshlrev_b32_e32 v248, 16, v186
	v_and_b32_e32 v249, 0xffff0000, v186
	v_pk_mul_f32 v[34:35], v[34:35], v[248:249]
	v_lshlrev_b32_e32 v250, 16, v187
	v_and_b32_e32 v251, 0xffff0000, v187
	v_pk_mul_f32 v[36:37], v[36:37], v[250:251]
	v_lshlrev_b32_e32 v248, 16, v158
	v_and_b32_e32 v249, 0xffff0000, v158
	v_pk_add_f32 v[38:39], v[38:39], v[248:249]
	v_lshlrev_b32_e32 v250, 16, v159
	v_and_b32_e32 v251, 0xffff0000, v159
	v_pk_add_f32 v[40:41], v[40:41], v[250:251]
	v_lshlrev_b32_e32 v248, 16, v160
	v_and_b32_e32 v249, 0xffff0000, v160
	v_pk_add_f32 v[34:35], v[34:35], v[248:249]
	v_lshlrev_b32_e32 v250, 16, v161
	v_and_b32_e32 v251, 0xffff0000, v161
	v_pk_add_f32 v[36:37], v[36:37], v[250:251]
	v_cvt_pk_bf16_f32 v158, v38, v39
	v_cvt_pk_bf16_f32 v159, v40, v41
	v_cvt_pk_bf16_f32 v160, v34, v35
	v_cvt_pk_bf16_f32 v161, v36, v37
	s_add_u32 s44, s46, 0x48000
	s_addc_u32 s45, s47, 0
	global_store_dwordx4 v167, v[158:161], s[44:45] offset:256
	s_add_u32 s44, s46, 0x58000
	s_addc_u32 s45, s47, 0
	global_load_dwordx4 v[184:187], v167, s[44:45] offset:256
	s_waitcnt vmcnt(6)
	v_lshlrev_b32_e32 v248, 16, v188
	v_and_b32_e32 v249, 0xffff0000, v188
	v_pk_mul_f32 v[30:31], v[30:31], v[248:249]
	v_lshlrev_b32_e32 v250, 16, v189
	v_and_b32_e32 v251, 0xffff0000, v189
	v_pk_mul_f32 v[32:33], v[32:33], v[250:251]
	v_lshlrev_b32_e32 v248, 16, v190
	v_and_b32_e32 v249, 0xffff0000, v190
	v_pk_mul_f32 v[26:27], v[26:27], v[248:249]
	v_lshlrev_b32_e32 v250, 16, v191
	v_and_b32_e32 v251, 0xffff0000, v191
	v_pk_mul_f32 v[28:29], v[28:29], v[250:251]
	v_lshlrev_b32_e32 v248, 16, v162
	v_and_b32_e32 v249, 0xffff0000, v162
	v_pk_add_f32 v[30:31], v[30:31], v[248:249]
	v_lshlrev_b32_e32 v250, 16, v163
	v_and_b32_e32 v251, 0xffff0000, v163
	v_pk_add_f32 v[32:33], v[32:33], v[250:251]
	v_lshlrev_b32_e32 v248, 16, v164
	v_and_b32_e32 v249, 0xffff0000, v164
	v_pk_add_f32 v[26:27], v[26:27], v[248:249]
	v_lshlrev_b32_e32 v250, 16, v165
	v_and_b32_e32 v251, 0xffff0000, v165
	v_pk_add_f32 v[28:29], v[28:29], v[250:251]
	v_cvt_pk_bf16_f32 v162, v30, v31
	v_cvt_pk_bf16_f32 v163, v32, v33
	v_cvt_pk_bf16_f32 v164, v26, v27
	v_cvt_pk_bf16_f32 v165, v28, v29
	s_add_u32 s44, s46, 0x50000
	s_addc_u32 s45, s47, 0
	global_store_dwordx4 v167, v[162:165], s[44:45]
	s_waitcnt vmcnt(5)
	v_lshlrev_b32_e32 v248, 16, v192
	v_and_b32_e32 v249, 0xffff0000, v192
	v_pk_mul_f32 v[22:23], v[22:23], v[248:249]
	v_lshlrev_b32_e32 v250, 16, v193
	v_and_b32_e32 v251, 0xffff0000, v193
	v_pk_mul_f32 v[24:25], v[24:25], v[250:251]
	v_lshlrev_b32_e32 v248, 16, v194
	v_and_b32_e32 v249, 0xffff0000, v194
	v_pk_mul_f32 v[18:19], v[18:19], v[248:249]
	v_lshlrev_b32_e32 v250, 16, v195
	v_and_b32_e32 v251, 0xffff0000, v195
	v_pk_mul_f32 v[20:21], v[20:21], v[250:251]
	v_lshlrev_b32_e32 v248, 16, v176
	v_and_b32_e32 v249, 0xffff0000, v176
	v_pk_add_f32 v[22:23], v[22:23], v[248:249]
	v_lshlrev_b32_e32 v250, 16, v177
	v_and_b32_e32 v251, 0xffff0000, v177
	v_pk_add_f32 v[24:25], v[24:25], v[250:251]
	v_lshlrev_b32_e32 v248, 16, v178
	v_and_b32_e32 v249, 0xffff0000, v178
	v_pk_add_f32 v[18:19], v[18:19], v[248:249]
	v_lshlrev_b32_e32 v250, 16, v179
	v_and_b32_e32 v251, 0xffff0000, v179
	v_pk_add_f32 v[20:21], v[20:21], v[250:251]
	v_cvt_pk_bf16_f32 v176, v22, v23
	v_cvt_pk_bf16_f32 v177, v24, v25
	v_cvt_pk_bf16_f32 v178, v18, v19
	v_cvt_pk_bf16_f32 v179, v20, v21
	s_add_u32 s44, s46, 0x50000
	s_addc_u32 s45, s47, 0
	global_store_dwordx4 v167, v[176:179], s[44:45] offset:256
	s_waitcnt vmcnt(4)
	v_lshlrev_b32_e32 v248, 16, v196
	v_and_b32_e32 v249, 0xffff0000, v196
	v_pk_mul_f32 v[14:15], v[14:15], v[248:249]
	v_lshlrev_b32_e32 v250, 16, v197
	v_and_b32_e32 v251, 0xffff0000, v197
	v_pk_mul_f32 v[16:17], v[16:17], v[250:251]
	v_lshlrev_b32_e32 v248, 16, v198
	v_and_b32_e32 v249, 0xffff0000, v198
	v_pk_mul_f32 v[10:11], v[10:11], v[248:249]
	v_lshlrev_b32_e32 v250, 16, v199
	v_and_b32_e32 v251, 0xffff0000, v199
	v_pk_mul_f32 v[12:13], v[12:13], v[250:251]
	v_lshlrev_b32_e32 v248, 16, v180
	v_and_b32_e32 v249, 0xffff0000, v180
	v_pk_add_f32 v[14:15], v[14:15], v[248:249]
	v_lshlrev_b32_e32 v250, 16, v181
	v_and_b32_e32 v251, 0xffff0000, v181
	v_pk_add_f32 v[16:17], v[16:17], v[250:251]
	v_lshlrev_b32_e32 v248, 16, v182
	v_and_b32_e32 v249, 0xffff0000, v182
	v_pk_add_f32 v[10:11], v[10:11], v[248:249]
	v_lshlrev_b32_e32 v250, 16, v183
	v_and_b32_e32 v251, 0xffff0000, v183
	v_pk_add_f32 v[12:13], v[12:13], v[250:251]
	v_cvt_pk_bf16_f32 v180, v14, v15
	v_cvt_pk_bf16_f32 v181, v16, v17
	v_cvt_pk_bf16_f32 v182, v10, v11
	v_cvt_pk_bf16_f32 v183, v12, v13
	s_add_u32 s44, s46, 0x58000
	s_addc_u32 s45, s47, 0
	global_store_dwordx4 v167, v[180:183], s[44:45]
	s_waitcnt vmcnt(3)
; DI float bf_lo(unsigned u) { return __uint_as_float(u << 16); }
; DI float bf_hi(unsigned u) { return __uint_as_float(u & 0xffff0000u); }
; #define PK8(v0, v1) ((u32x4){pk2((v0)[0], (v0)[1]), pk2((v0)[2], (v0)[3]), pk2((v1)[0], (v1)[1]), pk2((v1)[2], (v1)[3])})
;     DI void operator()(const f32x4 (&acc)[2][2][4][2], const Unit& u, int wr, int wc, int fr, int fq, int tid, LAS unsigned char* lds) const {
;     ...
;             for (int ai = 0; ai < 2; ++ai)
; #pragma unroll
;                 for (int m = 0; m < 4; ++m) { const int row = row0 + ai * 128 + m * 16;
; #pragma unroll
;                     for (int bj = 0; bj < 2; ++bj) { const u32x4 g = st[((ai * 4 + m) * 2 + bj) * 512];
;                         u32x4* d = (u32x4*)(dst + (size_t)row * 1024 + u.pn * 256 + lc0 + bj * 128);
;                         const f32x4 a0 = acc[ai][bj][m][0], a1 = acc[ai][bj][m][1];
;                         f32x4 r0 = {bf_lo(g.x) * a0[0], bf_hi(g.x) * a0[1], bf_lo(g.y) * a0[2], bf_hi(g.y) * a0[3]}, r1 = {bf_lo(g.z) * a1[0], bf_hi(g.z) * a1[1], bf_lo(g.w) * a1[2], bf_hi(g.w) * a1[3]};
;                         if (!first) { const u32x4 o = *d; r0[0] += bf_lo(o.x); r0[1] += bf_hi(o.x); r0[2] += bf_lo(o.y); r0[3] += bf_hi(o.y); r1[0] += bf_lo(o.z); r1[1] += bf_hi(o.z); r1[2] += bf_lo(o.w); r1[3] += bf_hi(o.w); }
;                         *d = PK8(r0, r1); } }
	v_lshlrev_b32_e32 v248, 16, v200
	v_and_b32_e32 v249, 0xffff0000, v200
	v_pk_mul_f32 v[6:7], v[6:7], v[248:249]
	v_lshlrev_b32_e32 v250, 16, v201
	v_and_b32_e32 v251, 0xffff0000, v201
	v_pk_mul_f32 v[8:9], v[8:9], v[250:251]
	v_lshlrev_b32_e32 v248, 16, v202
	v_and_b32_e32 v249, 0xffff0000, v202
	v_pk_mul_f32 v[2:3], v[2:3], v[248:249]
	v_lshlrev_b32_e32 v250, 16, v203
	v_and_b32_e32 v251, 0xffff0000, v203
	v_pk_mul_f32 v[4:5], v[4:5], v[250:251]
	v_lshlrev_b32_e32 v248, 16, v184
	v_and_b32_e32 v249, 0xffff0000, v184
	v_pk_add_f32 v[6:7], v[6:7], v[248:249]
	v_lshlrev_b32_e32 v250, 16, v185
	v_and_b32_e32 v251, 0xffff0000, v185
	v_pk_add_f32 v[8:9], v[8:9], v[250:251]
	v_lshlrev_b32_e32 v248, 16, v186
	v_and_b32_e32 v249, 0xffff0000, v186
	v_pk_add_f32 v[2:3], v[2:3], v[248:249]
	v_lshlrev_b32_e32 v250, 16, v187
	v_and_b32_e32 v251, 0xffff0000, v187
	v_pk_add_f32 v[4:5], v[4:5], v[250:251]
	v_cvt_pk_bf16_f32 v184, v6, v7
	v_cvt_pk_bf16_f32 v185, v8, v9
	v_cvt_pk_bf16_f32 v186, v2, v3
	v_cvt_pk_bf16_f32 v187, v4, v5
	s_add_u32 s44, s46, 0x58000
	s_addc_u32 s45, s47, 0
	global_store_dwordx4 v167, v[184:187], s[44:45] offset:256
	s_branch .Lbr_done
.Lbr_first:
	global_load_dwordx4 v[130:133], v166, s[42:43]
	s_add_u32 s44, s42, 0x2000
	s_addc_u32 s45, s43, 0
	global_load_dwordx4 v[134:137], v166, s[44:45]
	s_add_u32 s44, s42, 0x4000
	s_addc_u32 s45, s43, 0
	global_load_dwordx4 v[138:141], v166, s[44:45]
	s_add_u32 s44, s42, 0x6000
	s_addc_u32 s45, s43, 0
	global_load_dwordx4 v[142:145], v166, s[44:45]
	s_add_u32 s44, s42, 0x8000
	s_addc_u32 s45, s43, 0
	global_load_dwordx4 v[146:149], v166, s[44:45]
	s_add_u32 s44, s42, 0xa000
	s_addc_u32 s45, s43, 0
	global_load_dwordx4 v[150:153], v166, s[44:45]
	s_add_u32 s44, s42, 0xc000
	s_addc_u32 s45, s43, 0
	global_load_dwordx4 v[154:157], v166, s[44:45]
	s_add_u32 s44, s42, 0xe000
	s_addc_u32 s45, s43, 0
	global_load_dwordx4 v[158:161], v166, s[44:45]
	s_add_u32 s44, s42, 0x10000
	s_addc_u32 s45, s43, 0
	global_load_dwordx4 v[162:165], v166, s[44:45]
	s_add_u32 s44, s42, 0x12000
	s_addc_u32 s45, s43, 0
	global_load_dwordx4 v[176:179], v166, s[44:45]
	s_add_u32 s44, s42, 0x14000
	s_addc_u32 s45, s43, 0
	global_load_dwordx4 v[180:183], v166, s[44:45]
	s_add_u32 s44, s42, 0x16000
	s_addc_u32 s45, s43, 0
	global_load_dwordx4 v[184:187], v166, s[44:45]
	s_add_u32 s44, s42, 0x18000
	s_addc_u32 s45, s43, 0
	global_load_dwordx4 v[188:191], v166, s[44:45]
	s_add_u32 s44, s42, 0x1a000
	s_addc_u32 s45, s43, 0
	global_load_dwordx4 v[192:195], v166, s[44:45]
	s_add_u32 s44, s42, 0x1c000
	s_addc_u32 s45, s43, 0
	global_load_dwordx4 v[196:199], v166, s[44:45]
	s_add_u32 s44, s42, 0x1e000
	s_addc_u32 s45, s43, 0
	global_load_dwordx4 v[200:203], v166, s[44:45]
	s_waitcnt vmcnt(15)
	v_lshlrev_b32_e32 v248, 16, v130
	v_and_b32_e32 v249, 0xffff0000, v130
	v_pk_mul_f32 v[126:127], v[126:127], v[248:249]
	v_lshlrev_b32_e32 v250, 16, v131
	v_and_b32_e32 v251, 0xffff0000, v131
	v_pk_mul_f32 v[128:129], v[128:129], v[250:251]
	v_lshlrev_b32_e32 v248, 16, v132
	v_and_b32_e32 v249, 0xffff0000, v132
	v_pk_mul_f32 v[122:123], v[122:123], v[248:249]
	v_lshlrev_b32_e32 v250, 16, v133
	v_and_b32_e32 v251, 0xffff0000, v133
	v_pk_mul_f32 v[124:125], v[124:125], v[250:251]
	v_cvt_pk_bf16_f32 v130, v126, v127
	v_cvt_pk_bf16_f32 v131, v128, v129
	v_cvt_pk_bf16_f32 v132, v122, v123
	v_cvt_pk_bf16_f32 v133, v124, v125
	global_store_dwordx4 v167, v[130:133], s[46:47]
	s_waitcnt vmcnt(15)
	v_lshlrev_b32_e32 v248, 16, v134
	v_and_b32_e32 v249, 0xffff0000, v134
	v_pk_mul_f32 v[118:119], v[118:119], v[248:249]
	v_lshlrev_b32_e32 v250, 16, v135
	v_and_b32_e32 v251, 0xffff0000, v135
	v_pk_mul_f32 v[120:121], v[120:121], v[250:251]
	v_lshlrev_b32_e32 v248, 16, v136
	v_and_b32_e32 v249, 0xffff0000, v136
	v_pk_mul_f32 v[114:115], v[114:115], v[248:249]
	v_lshlrev_b32_e32 v250, 16, v137
	v_and_b32_e32 v251, 0xffff0000, v137
	v_pk_mul_f32 v[116:117], v[116:117], v[250:251]
	v_cvt_pk_bf16_f32 v134, v118, v119
	v_cvt_pk_bf16_f32 v135, v120, v121
	v_cvt_pk_bf16_f32 v136, v114, v115
	v_cvt_pk_bf16_f32 v137, v116, v117
	global_store_dwordx4 v167, v[134:137], s[46:47] offset:256
	s_waitcnt vmcnt(15)
	v_lshlrev_b32_e32 v248, 16, v138
	v_and_b32_e32 v249, 0xffff0000, v138
	v_pk_mul_f32 v[110:111], v[110:111], v[248:249]
	v_lshlrev_b32_e32 v250, 16, v139
	v_and_b32_e32 v251, 0xffff0000, v139
	v_pk_mul_f32 v[112:113], v[112:113], v[250:251]
	v_lshlrev_b32_e32 v248, 16, v140
	v_and_b32_e32 v249, 0xffff0000, v140
	v_pk_mul_f32 v[106:107], v[106:107], v[248:249]
	v_lshlrev_b32_e32 v250, 16, v141
	v_and_b32_e32 v251, 0xffff0000, v141
	v_pk_mul_f32 v[108:109], v[108:109], v[250:251]
	v_cvt_pk_bf16_f32 v138, v110, v111
	v_cvt_pk_bf16_f32 v139, v112, v113
	v_cvt_pk_bf16_f32 v140, v106, v107
	v_cvt_pk_bf16_f32 v141, v108, v109
	s_add_u32 s44, s46, 0x8000
	s_addc_u32 s45, s47, 0
	global_store_dwordx4 v167, v[138:141], s[44:45]
	s_waitcnt vmcnt(15)
	v_lshlrev_b32_e32 v248, 16, v142
	v_and_b32_e32 v249, 0xffff0000, v142
	v_pk_mul_f32 v[102:103], v[102:103], v[248:249]
	v_lshlrev_b32_e32 v250, 16, v143
	v_and_b32_e32 v251, 0xffff0000, v143
	v_pk_mul_f32 v[104:105], v[104:105], v[250:251]
	v_lshlrev_b32_e32 v248, 16, v144
	v_and_b32_e32 v249, 0xffff0000, v144
	v_pk_mul_f32 v[98:99], v[98:99], v[248:249]
	v_lshlrev_b32_e32 v250, 16, v145
	v_and_b32_e32 v251, 0xffff0000, v145
	v_pk_mul_f32 v[100:101], v[100:101], v[250:251]
	v_cvt_pk_bf16_f32 v142, v102, v103
	v_cvt_pk_bf16_f32 v143, v104, v105
	v_cvt_pk_bf16_f32 v144, v98, v99
	v_cvt_pk_bf16_f32 v145, v100, v101
	s_add_u32 s44, s46, 0x8000
	s_addc_u32 s45, s47, 0
	global_store_dwordx4 v167, v[142:145], s[44:45] offset:256
	s_waitcnt vmcnt(15)
; DI float bf_lo(unsigned u) { return __uint_as_float(u << 16); }
; DI float bf_hi(unsigned u) { return __uint_as_float(u & 0xffff0000u); }
; #define PK8(v0, v1) ((u32x4){pk2((v0)[0], (v0)[1]), pk2((v0)[2], (v0)[3]), pk2((v1)[0], (v1)[1]), pk2((v1)[2], (v1)[3])})
;     DI void operator()(const f32x4 (&acc)[2][2][4][2], const Unit& u, int wr, int wc, int fr, int fq, int tid, LAS unsigned char* lds) const {
;     ...
;             for (int ai = 0; ai < 2; ++ai)
; #pragma unroll
;                 for (int m = 0; m < 4; ++m) { const int row = row0 + ai * 128 + m * 16;
; #pragma unroll
;                     for (int bj = 0; bj < 2; ++bj) { const u32x4 g = st[((ai * 4 + m) * 2 + bj) * 512];
;                         u32x4* d = (u32x4*)(dst + (size_t)row * 1024 + u.pn * 256 + lc0 + bj * 128);
;                         const f32x4 a0 = acc[ai][bj][m][0], a1 = acc[ai][bj][m][1];
;                         f32x4 r0 = {bf_lo(g.x) * a0[0], bf_hi(g.x) * a0[1], bf_lo(g.y) * a0[2], bf_hi(g.y) * a0[3]}, r1 = {bf_lo(g.z) * a1[0], bf_hi(g.z) * a1[1], bf_lo(g.w) * a1[2], bf_hi(g.w) * a1[3]};
;                         if (!first) { const u32x4 o = *d; r0[0] += bf_lo(o.x); r0[1] += bf_hi(o.x); r0[2] += bf_lo(o.y); r0[3] += bf_hi(o.y); r1[0] += bf_lo(o.z); r1[1] += bf_hi(o.z); r1[2] += bf_lo(o.w); r1[3] += bf_hi(o.w); }
;                         *d = PK8(r0, r1); } }
	v_lshlrev_b32_e32 v248, 16, v146
	v_and_b32_e32 v249, 0xffff0000, v146
	v_pk_mul_f32 v[94:95], v[94:95], v[248:249]
	v_lshlrev_b32_e32 v250, 16, v147
	v_and_b32_e32 v251, 0xffff0000, v147
	v_pk_mul_f32 v[96:97], v[96:97], v[250:251]
	v_lshlrev_b32_e32 v248, 16, v148
	v_and_b32_e32 v249, 0xffff0000, v148
	v_pk_mul_f32 v[90:91], v[90:91], v[248:249]
	v_lshlrev_b32_e32 v250, 16, v149
	v_and_b32_e32 v251, 0xffff0000, v149
	v_pk_mul_f32 v[92:93], v[92:93], v[250:251]
	v_cvt_pk_bf16_f32 v146, v94, v95
	v_cvt_pk_bf16_f32 v147, v96, v97
	v_cvt_pk_bf16_f32 v148, v90, v91
	v_cvt_pk_bf16_f32 v149, v92, v93
	s_add_u32 s44, s46, 0x10000
	s_addc_u32 s45, s47, 0
	global_store_dwordx4 v167, v[146:149], s[44:45]
	s_waitcnt vmcnt(15)
	v_lshlrev_b32_e32 v248, 16, v150
	v_and_b32_e32 v249, 0xffff0000, v150
	v_pk_mul_f32 v[86:87], v[86:87], v[248:249]
	v_lshlrev_b32_e32 v250, 16, v151
	v_and_b32_e32 v251, 0xffff0000, v151
	v_pk_mul_f32 v[88:89], v[88:89], v[250:251]
	v_lshlrev_b32_e32 v248, 16, v152
	v_and_b32_e32 v249, 0xffff0000, v152
	v_pk_mul_f32 v[82:83], v[82:83], v[248:249]
	v_lshlrev_b32_e32 v250, 16, v153
	v_and_b32_e32 v251, 0xffff0000, v153
	v_pk_mul_f32 v[84:85], v[84:85], v[250:251]
	v_cvt_pk_bf16_f32 v150, v86, v87
	v_cvt_pk_bf16_f32 v151, v88, v89
	v_cvt_pk_bf16_f32 v152, v82, v83
	v_cvt_pk_bf16_f32 v153, v84, v85
	s_add_u32 s44, s46, 0x10000
	s_addc_u32 s45, s47, 0
	global_store_dwordx4 v167, v[150:153], s[44:45] offset:256
	s_waitcnt vmcnt(15)
	v_lshlrev_b32_e32 v248, 16, v154
	v_and_b32_e32 v249, 0xffff0000, v154
	v_pk_mul_f32 v[78:79], v[78:79], v[248:249]
	v_lshlrev_b32_e32 v250, 16, v155
	v_and_b32_e32 v251, 0xffff0000, v155
	v_pk_mul_f32 v[80:81], v[80:81], v[250:251]
	v_lshlrev_b32_e32 v248, 16, v156
	v_and_b32_e32 v249, 0xffff0000, v156
	v_pk_mul_f32 v[74:75], v[74:75], v[248:249]
	v_lshlrev_b32_e32 v250, 16, v157
	v_and_b32_e32 v251, 0xffff0000, v157
	v_pk_mul_f32 v[76:77], v[76:77], v[250:251]
	v_cvt_pk_bf16_f32 v154, v78, v79
	v_cvt_pk_bf16_f32 v155, v80, v81
	v_cvt_pk_bf16_f32 v156, v74, v75
	v_cvt_pk_bf16_f32 v157, v76, v77
	s_add_u32 s44, s46, 0x18000
	s_addc_u32 s45, s47, 0
	global_store_dwordx4 v167, v[154:157], s[44:45]
	s_waitcnt vmcnt(15)
	v_lshlrev_b32_e32 v248, 16, v158
	v_and_b32_e32 v249, 0xffff0000, v158
	v_pk_mul_f32 v[70:71], v[70:71], v[248:249]
	v_lshlrev_b32_e32 v250, 16, v159
	v_and_b32_e32 v251, 0xffff0000, v159
	v_pk_mul_f32 v[72:73], v[72:73], v[250:251]
	v_lshlrev_b32_e32 v248, 16, v160
	v_and_b32_e32 v249, 0xffff0000, v160
	v_pk_mul_f32 v[66:67], v[66:67], v[248:249]
	v_lshlrev_b32_e32 v250, 16, v161
	v_and_b32_e32 v251, 0xffff0000, v161
	v_pk_mul_f32 v[68:69], v[68:69], v[250:251]
	v_cvt_pk_bf16_f32 v158, v70, v71
	v_cvt_pk_bf16_f32 v159, v72, v73
	v_cvt_pk_bf16_f32 v160, v66, v67
	v_cvt_pk_bf16_f32 v161, v68, v69
	s_add_u32 s44, s46, 0x18000
	s_addc_u32 s45, s47, 0
	global_store_dwordx4 v167, v[158:161], s[44:45] offset:256
	s_waitcnt vmcnt(15)
	v_lshlrev_b32_e32 v248, 16, v162
	v_and_b32_e32 v249, 0xffff0000, v162
	v_pk_mul_f32 v[62:63], v[62:63], v[248:249]
	v_lshlrev_b32_e32 v250, 16, v163
	v_and_b32_e32 v251, 0xffff0000, v163
	v_pk_mul_f32 v[64:65], v[64:65], v[250:251]
	v_lshlrev_b32_e32 v248, 16, v164
	v_and_b32_e32 v249, 0xffff0000, v164
	v_pk_mul_f32 v[58:59], v[58:59], v[248:249]
	v_lshlrev_b32_e32 v250, 16, v165
	v_and_b32_e32 v251, 0xffff0000, v165
	v_pk_mul_f32 v[60:61], v[60:61], v[250:251]
	v_cvt_pk_bf16_f32 v162, v62, v63
	v_cvt_pk_bf16_f32 v163, v64, v65
	v_cvt_pk_bf16_f32 v164, v58, v59
	v_cvt_pk_bf16_f32 v165, v60, v61
	s_add_u32 s44, s46, 0x40000
	s_addc_u32 s45, s47, 0
	global_store_dwordx4 v167, v[162:165], s[44:45]
	s_waitcnt vmcnt(15)
	v_lshlrev_b32_e32 v248, 16, v176
	v_and_b32_e32 v249, 0xffff0000, v176
	v_pk_mul_f32 v[54:55], v[54:55], v[248:249]
	v_lshlrev_b32_e32 v250, 16, v177
	v_and_b32_e32 v251, 0xffff0000, v177
	v_pk_mul_f32 v[56:57], v[56:57], v[250:251]
	v_lshlrev_b32_e32 v248, 16, v178
	v_and_b32_e32 v249, 0xffff0000, v178
	v_pk_mul_f32 v[50:51], v[50:51], v[248:249]
	v_lshlrev_b32_e32 v250, 16, v179
	v_and_b32_e32 v251, 0xffff0000, v179
	v_pk_mul_f32 v[52:53], v[52:53], v[250:251]
	v_cvt_pk_bf16_f32 v176, v54, v55
	v_cvt_pk_bf16_f32 v177, v56, v57
	v_cvt_pk_bf16_f32 v178, v50, v51
	v_cvt_pk_bf16_f32 v179, v52, v53
	s_add_u32 s44, s46, 0x40000
	s_addc_u32 s45, s47, 0
	global_store_dwordx4 v167, v[176:179], s[44:45] offset:256
	s_waitcnt vmcnt(15)
	v_lshlrev_b32_e32 v248, 16, v180
	v_and_b32_e32 v249, 0xffff0000, v180
	v_pk_mul_f32 v[46:47], v[46:47], v[248:249]
	v_lshlrev_b32_e32 v250, 16, v181
	v_and_b32_e32 v251, 0xffff0000, v181
	v_pk_mul_f32 v[48:49], v[48:49], v[250:251]
	v_lshlrev_b32_e32 v248, 16, v182
	v_and_b32_e32 v249, 0xffff0000, v182
	v_pk_mul_f32 v[42:43], v[42:43], v[248:249]
	v_lshlrev_b32_e32 v250, 16, v183
	v_and_b32_e32 v251, 0xffff0000, v183
	v_pk_mul_f32 v[44:45], v[44:45], v[250:251]
	v_cvt_pk_bf16_f32 v180, v46, v47
	v_cvt_pk_bf16_f32 v181, v48, v49
	v_cvt_pk_bf16_f32 v182, v42, v43
	v_cvt_pk_bf16_f32 v183, v44, v45
	s_add_u32 s44, s46, 0x48000
	s_addc_u32 s45, s47, 0
	global_store_dwordx4 v167, v[180:183], s[44:45]
	s_waitcnt vmcnt(15)
	v_lshlrev_b32_e32 v248, 16, v184
	v_and_b32_e32 v249, 0xffff0000, v184
	v_pk_mul_f32 v[38:39], v[38:39], v[248:249]
	v_lshlrev_b32_e32 v250, 16, v185
	v_and_b32_e32 v251, 0xffff0000, v185
	v_pk_mul_f32 v[40:41], v[40:41], v[250:251]
	v_lshlrev_b32_e32 v248, 16, v186
	v_and_b32_e32 v249, 0xffff0000, v186
	v_pk_mul_f32 v[34:35], v[34:35], v[248:249]
	v_lshlrev_b32_e32 v250, 16, v187
	v_and_b32_e32 v251, 0xffff0000, v187
	v_pk_mul_f32 v[36:37], v[36:37], v[250:251]
	v_cvt_pk_bf16_f32 v184, v38, v39
	v_cvt_pk_bf16_f32 v185, v40, v41
	v_cvt_pk_bf16_f32 v186, v34, v35
	v_cvt_pk_bf16_f32 v187, v36, v37
	s_add_u32 s44, s46, 0x48000
	s_addc_u32 s45, s47, 0
	global_store_dwordx4 v167, v[184:187], s[44:45] offset:256
	s_waitcnt vmcnt(15)
; #define LAS __attribute__((address_space(3)))
; DI float bf_lo(unsigned u) { return __uint_as_float(u << 16); }
; DI float bf_hi(unsigned u) { return __uint_as_float(u & 0xffff0000u); }
; DI float sum16(const float* p) { const f32x4 a = *(const f32x4*)p, b = *(const f32x4*)(p + 4), c = *(const f32x4*)(p + 8), d = *(const f32x4*)(p + 12); return (((a[0] + a[1]) + (a[2] + a[3])) + ((b[0] + b[1]) + (b[2] + b[3]))) + (((c[0] + c[1]) + (c[2] + c[3])) + ((d[0] + d[1]) + (d[2] + d[3]))); }
; DI float sum12(const float* p) { const f32x4 a = *(const f32x4*)p, b = *(const f32x4*)(p + 4), c = *(const f32x4*)(p + 8); return (((a[0] + a[1]) + (a[2] + a[3])) + ((b[0] + b[1]) + (b[2] + b[3]))) + ((c[0] + c[1]) + (c[2] + c[3])); }
; DI float sum4(const float* p) { const f32x4 a = *(const f32x4*)p; return (a[0] + a[1]) + (a[2] + a[3]); }
;     template <int NS> DI void rowstat(float (&rs)[2][4], const float* parts, float inv_n, float mul, int rowbase_wave, LAS float* buf, int lane, int fr) const {
; #pragma unroll
;         for (int h = 0; h < 2; ++h) { const float* pp = parts + (size_t)(rowbase_wave + h * 128 + lane) * (NS == 4 ? 4 : 16);
;             const float sm = NS == 16 ? sum16(pp) : (NS == 12 ? sum12(pp) : sum4(pp)); buf[h * 64 + lane] = __builtin_amdgcn_rsqf(sm * inv_n + EPS) * mul; }
;     DI void operator()(const f32x4 (&acc)[2][2][4][2], const Unit& u, int wr, int wc, int fr, int fq, int tid, LAS unsigned char* lds) const {
;     ...
;             for (int ai = 0; ai < 2; ++ai)
; #pragma unroll
;                 for (int m = 0; m < 4; ++m) { const int row = row0 + ai * 128 + m * 16;
; #pragma unroll
;                     for (int bj = 0; bj < 2; ++bj) { const u32x4 g = st[((ai * 4 + m) * 2 + bj) * 512];
;                         u32x4* d = (u32x4*)(dst + (size_t)row * 1024 + u.pn * 256 + lc0 + bj * 128);
;                         const f32x4 a0 = acc[ai][bj][m][0], a1 = acc[ai][bj][m][1];
;                         f32x4 r0 = {bf_lo(g.x) * a0[0], bf_hi(g.x) * a0[1], bf_lo(g.y) * a0[2], bf_hi(g.y) * a0[3]}, r1 = {bf_lo(g.z) * a1[0], bf_hi(g.z) * a1[1], bf_lo(g.w) * a1[2], bf_hi(g.w) * a1[3]};
;                         if (!first) { const u32x4 o = *d; r0[0] += bf_lo(o.x); r0[1] += bf_hi(o.x); r0[2] += bf_lo(o.y); r0[3] += bf_hi(o.y); r1[0] += bf_lo(o.z); r1[1] += bf_hi(o.z); r1[2] += bf_lo(o.w); r1[3] += bf_hi(o.w); }
;                         *d = PK8(r0, r1); } }
	v_lshlrev_b32_e32 v248, 16, v188
	v_and_b32_e32 v249, 0xffff0000, v188
	v_pk_mul_f32 v[30:31], v[30:31], v[248:249]
	v_lshlrev_b32_e32 v250, 16, v189
	v_and_b32_e32 v251, 0xffff0000, v189
	v_pk_mul_f32 v[32:33], v[32:33], v[250:251]
	v_lshlrev_b32_e32 v248, 16, v190
	v_and_b32_e32 v249, 0xffff0000, v190
	v_pk_mul_f32 v[26:27], v[26:27], v[248:249]
	v_lshlrev_b32_e32 v250, 16, v191
	v_and_b32_e32 v251, 0xffff0000, v191
	v_pk_mul_f32 v[28:29], v[28:29], v[250:251]
	v_cvt_pk_bf16_f32 v188, v30, v31
	v_cvt_pk_bf16_f32 v189, v32, v33
	v_cvt_pk_bf16_f32 v190, v26, v27
	v_cvt_pk_bf16_f32 v191, v28, v29
	s_add_u32 s44, s46, 0x50000
	s_addc_u32 s45, s47, 0
	global_store_dwordx4 v167, v[188:191], s[44:45]
	s_waitcnt vmcnt(15)
	v_lshlrev_b32_e32 v248, 16, v192
	v_and_b32_e32 v249, 0xffff0000, v192
	v_pk_mul_f32 v[22:23], v[22:23], v[248:249]
	v_lshlrev_b32_e32 v250, 16, v193
	v_and_b32_e32 v251, 0xffff0000, v193
	v_pk_mul_f32 v[24:25], v[24:25], v[250:251]
	v_lshlrev_b32_e32 v248, 16, v194
	v_and_b32_e32 v249, 0xffff0000, v194
	v_pk_mul_f32 v[18:19], v[18:19], v[248:249]
	v_lshlrev_b32_e32 v250, 16, v195
	v_and_b32_e32 v251, 0xffff0000, v195
	v_pk_mul_f32 v[20:21], v[20:21], v[250:251]
	v_cvt_pk_bf16_f32 v192, v22, v23
	v_cvt_pk_bf16_f32 v193, v24, v25
	v_cvt_pk_bf16_f32 v194, v18, v19
	v_cvt_pk_bf16_f32 v195, v20, v21
	s_add_u32 s44, s46, 0x50000
	s_addc_u32 s45, s47, 0
	global_store_dwordx4 v167, v[192:195], s[44:45] offset:256
	s_waitcnt vmcnt(15)
	v_lshlrev_b32_e32 v248, 16, v196
	v_and_b32_e32 v249, 0xffff0000, v196
	v_pk_mul_f32 v[14:15], v[14:15], v[248:249]
	v_lshlrev_b32_e32 v250, 16, v197
	v_and_b32_e32 v251, 0xffff0000, v197
	v_pk_mul_f32 v[16:17], v[16:17], v[250:251]
	v_lshlrev_b32_e32 v248, 16, v198
	v_and_b32_e32 v249, 0xffff0000, v198
	v_pk_mul_f32 v[10:11], v[10:11], v[248:249]
	v_lshlrev_b32_e32 v250, 16, v199
	v_and_b32_e32 v251, 0xffff0000, v199
	v_pk_mul_f32 v[12:13], v[12:13], v[250:251]
	v_cvt_pk_bf16_f32 v196, v14, v15
	v_cvt_pk_bf16_f32 v197, v16, v17
	v_cvt_pk_bf16_f32 v198, v10, v11
	v_cvt_pk_bf16_f32 v199, v12, v13
	s_add_u32 s44, s46, 0x58000
	s_addc_u32 s45, s47, 0
	global_store_dwordx4 v167, v[196:199], s[44:45]
	s_waitcnt vmcnt(15)
	v_lshlrev_b32_e32 v248, 16, v200
	v_and_b32_e32 v249, 0xffff0000, v200
	v_pk_mul_f32 v[6:7], v[6:7], v[248:249]
	v_lshlrev_b32_e32 v250, 16, v201
	v_and_b32_e32 v251, 0xffff0000, v201
	v_pk_mul_f32 v[8:9], v[8:9], v[250:251]
	v_lshlrev_b32_e32 v248, 16, v202
	v_and_b32_e32 v249, 0xffff0000, v202
	v_pk_mul_f32 v[2:3], v[2:3], v[248:249]
	v_lshlrev_b32_e32 v250, 16, v203
	v_and_b32_e32 v251, 0xffff0000, v203
	v_pk_mul_f32 v[4:5], v[4:5], v[250:251]
	v_cvt_pk_bf16_f32 v200, v6, v7
	v_cvt_pk_bf16_f32 v201, v8, v9
	v_cvt_pk_bf16_f32 v202, v2, v3
	v_cvt_pk_bf16_f32 v203, v4, v5
	s_add_u32 s44, s46, 0x58000
	s_addc_u32 s45, s47, 0
	global_store_dwordx4 v167, v[200:203], s[44:45] offset:256
.Lbr_done:
	s_mov_b64 s[42:43], 0
.LBB0_500:
	s_and_b64 vcc, exec, s[42:43]
	s_cbranch_vccz .LBB0_502
	v_mov_b32_e32 v148, v231
	s_waitcnt lgkmcnt(0)
	v_mov_b32_e32 v0, v229
	v_mov_b32_e32 v131, v230
	v_readlane_b32 s2, v252, 1
	v_lshlrev_b32_e32 v130, 3, v148
	v_and_b32_e32 v130, 0xfffffe00, v130
	v_add_u32_e32 v152, s2, v130
	s_add_u32 s2, s50, 0x1000000
	s_addc_u32 s43, s51, 0
	s_sub_u32 s42, s66, s2
	v_and_b32_e32 v132, 63, v148
	s_subb_u32 s43, s67, s43
	s_lshr_b64 s[42:43], s[42:43], 11
	v_or_b32_e32 v150, s54, v132
	s_add_i32 s2, s24, s42
	v_ashrrev_i32_e32 v151, 31, v150
	v_lshl_add_u32 v130, v0, 3, s2
	v_lshl_add_u32 v0, v132, 2, v152
	v_lshlrev_b64 v[132:133], 6, v[150:151]
	v_lshl_add_u64 v[144:145], s[18:19], 0, v[132:133]
	global_load_dwordx4 v[132:135], v[144:145], off offset:48
	global_load_dwordx4 v[136:139], v[144:145], off offset:32
	global_load_dwordx4 v[140:143], v[144:145], off offset:16
	s_nop 0
	global_load_dwordx4 v[144:147], v[144:145], off
	s_mul_i32 s42, s14, 0x1d00
	s_ashr_i32 s43, s42, 31
	s_lshl_b64 s[42:43], s[42:43], 2
	s_add_u32 s42, s57, s42
	s_addc_u32 s43, s86, s43
	v_ashrrev_i32_e32 v149, 31, v148
	s_mov_b32 s2, 0x17a00000
	s_waitcnt vmcnt(0)
	v_add_f32_e32 v132, v132, v133
	v_add_f32_e32 v136, v136, v137
	v_add_f32_e32 v140, v140, v141
	v_add_f32_e32 v144, v144, v145
	v_add_f32_e32 v145, v146, v147
	v_add_f32_e32 v141, v142, v143
	v_add_f32_e32 v137, v138, v139
	v_add_f32_e32 v133, v134, v135
	v_add_f32_e32 v144, v144, v145
	v_add_f32_e32 v140, v140, v141
	v_add_f32_e32 v136, v136, v137
	v_add_f32_e32 v132, v132, v133
	v_add_f32_e32 v140, v144, v140
	v_add_f32_e32 v132, v136, v132
	v_add_f32_e32 v132, v140, v132
	v_fmamk_f32 v132, v132, 0x3a800000, v212
	v_rsq_f32_e32 v151, v132
	v_add_u32_e32 v132, 0x80, v150
	v_ashrrev_i32_e32 v133, 31, v132
	v_lshlrev_b64 v[132:133], 6, v[132:133]
	v_lshl_add_u64 v[144:145], s[18:19], 0, v[132:133]
	global_load_dwordx4 v[132:135], v[144:145], off offset:48
	global_load_dwordx4 v[136:139], v[144:145], off offset:32
	global_load_dwordx4 v[140:143], v[144:145], off offset:16
	s_nop 0
	global_load_dwordx4 v[144:147], v[144:145], off
	s_waitcnt vmcnt(3)
	v_add_f32_e32 v132, v132, v133
	s_waitcnt vmcnt(2)
	v_add_f32_e32 v136, v136, v137
	s_waitcnt vmcnt(1)
	v_add_f32_e32 v140, v140, v141
	s_waitcnt vmcnt(0)
; #define LAS __attribute__((address_space(3)))
; DI float sigmoidf_(float x) { return __builtin_amdgcn_rcpf(1.f + fast_exp(-x)); }
; DI float sum16(const float* p) { const f32x4 a = *(const f32x4*)p, b = *(const f32x4*)(p + 4), c = *(const f32x4*)(p + 8), d = *(const f32x4*)(p + 12); return (((a[0] + a[1]) + (a[2] + a[3])) + ((b[0] + b[1]) + (b[2] + b[3]))) + (((c[0] + c[1]) + (c[2] + c[3])) + ((d[0] + d[1]) + (d[2] + d[3]))); }
; DI float sum12(const float* p) { const f32x4 a = *(const f32x4*)p, b = *(const f32x4*)(p + 4), c = *(const f32x4*)(p + 8); return (((a[0] + a[1]) + (a[2] + a[3])) + ((b[0] + b[1]) + (b[2] + b[3]))) + ((c[0] + c[1]) + (c[2] + c[3])); }
; DI float sum4(const float* p) { const f32x4 a = *(const f32x4*)p; return (a[0] + a[1]) + (a[2] + a[3]); }
;     template <int NS> DI void rowstat(float (&rs)[2][4], const float* parts, float inv_n, float mul, int rowbase_wave, LAS float* buf, int lane, int fr) const {
; #pragma unroll
;         for (int h = 0; h < 2; ++h) { const float* pp = parts + (size_t)(rowbase_wave + h * 128 + lane) * (NS == 4 ? 4 : 16);
;             const float sm = NS == 16 ? sum16(pp) : (NS == 12 ? sum12(pp) : sum4(pp)); buf[h * 64 + lane] = __builtin_amdgcn_rsqf(sm * inv_n + EPS) * mul; }
; #pragma unroll
;         for (int ai = 0; ai < 2; ++ai)
; #pragma unroll
;             for (int m = 0; m < 4; ++m) rs[ai][m] = buf[ai * 64 + m * 16 + fr];
;     DI void operator()(const f32x4 (&acc)[2][2][4][2], const Unit& u, int wr, int wc, int fr, int fq, int tid, LAS unsigned char* lds) const {
;     ...
;             f32x4 bv[2][2];
; #pragma unroll
;             for (int bj = 0; bj < 2; ++bj)
; #pragma unroll
;                 for (int n = 0; n < 2; ++n) bv[bj][n] = *(const f32x4*)(bias1 + bidx * NWIN + gcol + bj * 128 + n * 4);
; #pragma unroll
;             for (int ai = 0; ai < 2; ++ai)
; #pragma unroll
;                 for (int m = 0; m < 4; ++m)
; #pragma unroll
;                     for (int bj = 0; bj < 2; ++bj) { f32x4 g0, g1;
;                         const f32x4 a0 = acc[ai][bj][m][0] * rs[ai][m] + bv[bj][0], a1 = acc[ai][bj][m][1] * rs[ai][m] + bv[bj][1];
; #pragma unroll
;                         for (int e = 0; e < 4; ++e) { g0[e] = sigmoidf_(a0[e]); g1[e] = sigmoidf_(a1[e]); }
;                         st[((ai * 4 + m) * 2 + bj) * 512] = PK8(g0, g1); }
	v_add_f32_e32 v144, v144, v145
	v_add_f32_e32 v145, v146, v147
	v_add_f32_e32 v141, v142, v143
	v_add_f32_e32 v137, v138, v139
	v_add_f32_e32 v133, v134, v135
	v_add_f32_e32 v144, v144, v145
	v_add_f32_e32 v140, v140, v141
	v_add_f32_e32 v136, v136, v137
	v_add_f32_e32 v132, v132, v133
	v_add_f32_e32 v140, v144, v140
	v_add_f32_e32 v132, v136, v132
	v_add_f32_e32 v132, v140, v132
	v_fmamk_f32 v132, v132, 0x3a800000, v212
	v_rsq_f32_e32 v132, v132
	ds_write2st64_b32 v0, v151, v132 offset1:1
	v_lshl_add_u32 v0, v131, 2, v152
	v_ashrrev_i32_e32 v131, 31, v130
	v_lshl_add_u64 v[134:135], v[130:131], 2, s[42:43]
	ds_read2_b32 v[154:155], v0 offset1:16
	ds_read2_b32 v[152:153], v0 offset0:32 offset1:48
	ds_read2_b32 v[150:151], v0 offset0:64 offset1:80
	ds_read2_b32 v[146:147], v0 offset0:96 offset1:112
	global_load_dwordx4 v[138:141], v[134:135], off offset:16
	global_load_dwordx4 v[142:145], v[134:135], off
	global_load_dwordx4 v[130:133], v[134:135], off offset:528
	s_nop 0
	global_load_dwordx4 v[134:137], v[134:135], off offset:512
	v_readlane_b32 s42, v254, 21
	v_readlane_b32 s43, v254, 22
	s_add_u32 s42, s50, s42
	s_addc_u32 s43, s51, s43
	v_lshl_add_u64 v[148:149], v[148:149], 4, s[42:43]
	s_waitcnt vmcnt(3) lgkmcnt(3)
	v_fma_f32 v156, v122, v154, v138
	v_fma_f32 v157, v123, v154, v139
	v_mul_f32_e32 v156, 0xbfb8aa3b, v156
	v_mul_f32_e32 v157, 0xbfb8aa3b, v157
	v_exp_f32_e32 v156, v156
	v_exp_f32_e32 v157, v157
	v_fma_f32 v160, v124, v154, v140
	v_fma_f32 v162, v125, v154, v141
	v_add_f32_e32 v156, 1.0, v156
	v_add_f32_e32 v157, 1.0, v157
	s_waitcnt vmcnt(2)
	v_fma_f32 v0, v126, v154, v142
	v_rcp_f32_e32 v158, v156
	v_fma_f32 v156, v127, v154, v143
	v_rcp_f32_e32 v159, v157
	v_fma_f32 v157, v128, v154, v144
	v_mul_f32_e32 v160, 0xbfb8aa3b, v160
	v_fma_f32 v161, v129, v154, v145
	v_mul_f32_e32 v162, 0xbfb8aa3b, v162
	v_mul_f32_e32 v0, 0xbfb8aa3b, v0
	v_mul_f32_e32 v156, 0xbfb8aa3b, v156
	v_mul_f32_e32 v157, 0xbfb8aa3b, v157
	v_exp_f32_e32 v160, v160
	v_mul_f32_e32 v161, 0xbfb8aa3b, v161
	v_exp_f32_e32 v162, v162
	v_exp_f32_e32 v0, v0
	v_exp_f32_e32 v156, v156
	v_exp_f32_e32 v157, v157
	v_exp_f32_e32 v161, v161
	v_add_f32_e32 v160, 1.0, v160
	v_add_f32_e32 v162, 1.0, v162
	v_add_f32_e32 v0, 1.0, v0
	v_add_f32_e32 v156, 1.0, v156
	v_add_f32_e32 v157, 1.0, v157
	v_rcp_f32_e32 v160, v160
	v_add_f32_e32 v161, 1.0, v161
	v_rcp_f32_e32 v162, v162
	v_rcp_f32_e32 v0, v0
	v_rcp_f32_e32 v156, v156
	v_rcp_f32_e32 v157, v157
	v_rcp_f32_e32 v161, v161
	v_cvt_pk_bf16_f32 v158, v158, v159
	v_cvt_pk_bf16_f32 v159, v160, v162
	v_add_co_u32_e32 v160, vcc, s2, v148
	v_cvt_pk_bf16_f32 v156, v0, v156
	v_cvt_pk_bf16_f32 v157, v157, v161
	v_addc_co_u32_e32 v161, vcc, 0, v149, vcc
	global_store_dwordx4 v[160:161], v[156:159], off
	s_waitcnt vmcnt(1)
	v_fma_f32 v0, v118, v154, v134
	v_fma_f32 v160, v116, v154, v132
	v_fma_f32 v156, v114, v154, v130
	v_fma_f32 v157, v115, v154, v131
	v_mul_f32_e32 v156, 0xbfb8aa3b, v156
	v_mul_f32_e32 v157, 0xbfb8aa3b, v157
	v_exp_f32_e32 v156, v156
	v_exp_f32_e32 v157, v157
	v_fma_f32 v161, v121, v154, v137
	v_mul_f32_e32 v160, 0xbfb8aa3b, v160
	v_add_f32_e32 v156, 1.0, v156
	v_add_f32_e32 v157, 1.0, v157
	v_rcp_f32_e32 v158, v156
	v_fma_f32 v156, v119, v154, v135
	v_rcp_f32_e32 v159, v157
	v_fma_f32 v157, v120, v154, v136
	v_fma_f32 v154, v117, v154, v133
	v_mul_f32_e32 v154, 0xbfb8aa3b, v154
	v_mul_f32_e32 v0, 0xbfb8aa3b, v0
	v_mul_f32_e32 v156, 0xbfb8aa3b, v156
	v_mul_f32_e32 v157, 0xbfb8aa3b, v157
	v_exp_f32_e32 v160, v160
	v_mul_f32_e32 v161, 0xbfb8aa3b, v161
	v_exp_f32_e32 v154, v154
	v_exp_f32_e32 v0, v0
	v_exp_f32_e32 v156, v156
	v_exp_f32_e32 v157, v157
	v_exp_f32_e32 v161, v161
	v_add_f32_e32 v160, 1.0, v160
	v_add_f32_e32 v154, 1.0, v154
	v_add_f32_e32 v0, 1.0, v0
	v_add_f32_e32 v156, 1.0, v156
	v_add_f32_e32 v157, 1.0, v157
	v_rcp_f32_e32 v160, v160
	v_add_f32_e32 v161, 1.0, v161
	v_rcp_f32_e32 v154, v154
	v_rcp_f32_e32 v0, v0
	v_rcp_f32_e32 v156, v156
	v_rcp_f32_e32 v157, v157
	v_rcp_f32_e32 v161, v161
	s_mov_b32 s2, 0x17a02000
	v_cvt_pk_bf16_f32 v158, v158, v159
	v_cvt_pk_bf16_f32 v159, v160, v154
	v_add_co_u32_e32 v160, vcc, s2, v148
	v_cvt_pk_bf16_f32 v156, v0, v156
	v_cvt_pk_bf16_f32 v157, v157, v161
	v_addc_co_u32_e32 v161, vcc, 0, v149, vcc
	global_store_dwordx4 v[160:161], v[156:159], off
	v_fma_f32 v154, v106, v155, v138
	v_mul_f32_e32 v154, 0xbfb8aa3b, v154
	v_fma_f32 v157, v107, v155, v139
	v_mul_f32_e32 v157, 0xbfb8aa3b, v157
	v_exp_f32_e32 v157, v157
	v_exp_f32_e32 v154, v154
	v_fma_f32 v160, v113, v155, v145
	v_fma_f32 v0, v110, v155, v142
	v_add_f32_e32 v157, 1.0, v157
	v_rcp_f32_e32 v158, v157
	v_fma_f32 v157, v112, v155, v144
	v_fma_f32 v156, v111, v155, v143
	v_mul_f32_e32 v157, 0xbfb8aa3b, v157
	v_fma_f32 v159, v108, v155, v140
	v_mul_f32_e32 v160, 0xbfb8aa3b, v160
	v_fma_f32 v161, v109, v155, v141
	v_mul_f32_e32 v0, 0xbfb8aa3b, v0
	v_add_f32_e32 v154, 1.0, v154
	v_mul_f32_e32 v156, 0xbfb8aa3b, v156
	v_exp_f32_e32 v157, v157
	v_mul_f32_e32 v159, 0xbfb8aa3b, v159
	v_exp_f32_e32 v160, v160
	v_mul_f32_e32 v161, 0xbfb8aa3b, v161
	v_exp_f32_e32 v0, v0
	v_rcp_f32_e32 v154, v154
	v_exp_f32_e32 v156, v156
	v_exp_f32_e32 v159, v159
	v_exp_f32_e32 v161, v161
	v_add_f32_e32 v157, 1.0, v157
	v_add_f32_e32 v160, 1.0, v160
	v_add_f32_e32 v0, 1.0, v0
	v_add_f32_e32 v156, 1.0, v156
	v_rcp_f32_e32 v157, v157
	v_add_f32_e32 v159, 1.0, v159
	v_rcp_f32_e32 v160, v160
	v_add_f32_e32 v161, 1.0, v161
	v_cvt_pk_bf16_f32 v158, v154, v158
	v_fma_f32 v154, v98, v155, v130
	v_rcp_f32_e32 v0, v0
	v_rcp_f32_e32 v156, v156
	v_rcp_f32_e32 v159, v159
	v_rcp_f32_e32 v161, v161
	v_mul_f32_e32 v154, 0xbfb8aa3b, v154
	v_exp_f32_e32 v154, v154
; DI float sigmoidf_(float x) { return __builtin_amdgcn_rcpf(1.f + fast_exp(-x)); }
; #define PK8(v0, v1) ((u32x4){pk2((v0)[0], (v0)[1]), pk2((v0)[2], (v0)[3]), pk2((v1)[0], (v1)[1]), pk2((v1)[2], (v1)[3])})
;     DI void operator()(const f32x4 (&acc)[2][2][4][2], const Unit& u, int wr, int wc, int fr, int fq, int tid, LAS unsigned char* lds) const {
;     ...
; #pragma unroll
;             for (int ai = 0; ai < 2; ++ai)
; #pragma unroll
;                 for (int m = 0; m < 4; ++m)
; #pragma unroll
;                     for (int bj = 0; bj < 2; ++bj) { f32x4 g0, g1;
;                         const f32x4 a0 = acc[ai][bj][m][0] * rs[ai][m] + bv[bj][0], a1 = acc[ai][bj][m][1] * rs[ai][m] + bv[bj][1];
; #pragma unroll
;                         for (int e = 0; e < 4; ++e) { g0[e] = sigmoidf_(a0[e]); g1[e] = sigmoidf_(a1[e]); }
;                         st[((ai * 4 + m) * 2 + bj) * 512] = PK8(g0, g1); }
	s_mov_b32 s2, 0x17a04000
	v_cvt_pk_bf16_f32 v157, v157, v160
	v_add_co_u32_e32 v160, vcc, s2, v148
	v_cvt_pk_bf16_f32 v156, v0, v156
	v_cvt_pk_bf16_f32 v159, v159, v161
	v_addc_co_u32_e32 v161, vcc, 0, v149, vcc
	global_store_dwordx4 v[160:161], v[156:159], off
	v_add_f32_e32 v154, 1.0, v154
	v_fma_f32 v160, v105, v155, v137
	v_fma_f32 v158, v104, v155, v136
	v_fma_f32 v0, v102, v155, v134
	v_rcp_f32_e32 v156, v154
	v_fma_f32 v154, v103, v155, v135
	v_fma_f32 v157, v99, v155, v131
	v_mul_f32_e32 v158, 0xbfb8aa3b, v158
	v_fma_f32 v159, v100, v155, v132
	v_mul_f32_e32 v160, 0xbfb8aa3b, v160
	v_fma_f32 v155, v101, v155, v133
	v_mul_f32_e32 v0, 0xbfb8aa3b, v0
	v_mul_f32_e32 v154, 0xbfb8aa3b, v154
	v_mul_f32_e32 v157, 0xbfb8aa3b, v157
	v_exp_f32_e32 v158, v158
	v_mul_f32_e32 v159, 0xbfb8aa3b, v159
	v_exp_f32_e32 v160, v160
	v_mul_f32_e32 v155, 0xbfb8aa3b, v155
	v_exp_f32_e32 v0, v0
	v_exp_f32_e32 v154, v154
	v_exp_f32_e32 v157, v157
	v_exp_f32_e32 v159, v159
	v_exp_f32_e32 v155, v155
	v_add_f32_e32 v158, 1.0, v158
	v_add_f32_e32 v160, 1.0, v160
	v_add_f32_e32 v0, 1.0, v0
	v_add_f32_e32 v154, 1.0, v154
	v_add_f32_e32 v157, 1.0, v157
	v_rcp_f32_e32 v158, v158
	v_add_f32_e32 v159, 1.0, v159
	v_rcp_f32_e32 v160, v160
	v_add_f32_e32 v155, 1.0, v155
	v_rcp_f32_e32 v0, v0
	v_rcp_f32_e32 v154, v154
	v_rcp_f32_e32 v157, v157
	v_rcp_f32_e32 v159, v159
	v_rcp_f32_e32 v161, v155
	s_mov_b32 s2, 0x17a06000
	v_cvt_pk_bf16_f32 v155, v158, v160
	v_add_co_u32_e32 v158, vcc, s2, v148
	v_cvt_pk_bf16_f32 v154, v0, v154
	v_cvt_pk_bf16_f32 v156, v156, v157
	v_cvt_pk_bf16_f32 v157, v159, v161
	v_addc_co_u32_e32 v159, vcc, 0, v149, vcc
	global_store_dwordx4 v[158:159], v[154:157], off
	s_waitcnt lgkmcnt(2)
	v_fma_f32 v158, v92, v152, v140
	v_fma_f32 v160, v93, v152, v141
	v_fma_f32 v154, v90, v152, v138
	v_fma_f32 v155, v91, v152, v139
	v_mul_f32_e32 v154, 0xbfb8aa3b, v154
	v_mul_f32_e32 v155, 0xbfb8aa3b, v155
	v_exp_f32_e32 v154, v154
	v_exp_f32_e32 v155, v155
	v_fma_f32 v0, v94, v152, v142
	v_mul_f32_e32 v158, 0xbfb8aa3b, v158
	v_add_f32_e32 v154, 1.0, v154
	v_add_f32_e32 v155, 1.0, v155
	v_rcp_f32_e32 v156, v154
	v_fma_f32 v154, v95, v152, v143
	v_rcp_f32_e32 v157, v155
	v_fma_f32 v155, v96, v152, v144
	v_fma_f32 v159, v97, v152, v145
	v_mul_f32_e32 v160, 0xbfb8aa3b, v160
	v_mul_f32_e32 v0, 0xbfb8aa3b, v0
	v_mul_f32_e32 v154, 0xbfb8aa3b, v154
	v_mul_f32_e32 v155, 0xbfb8aa3b, v155
	v_exp_f32_e32 v158, v158
	v_mul_f32_e32 v159, 0xbfb8aa3b, v159
	v_exp_f32_e32 v160, v160
	v_exp_f32_e32 v0, v0
	v_exp_f32_e32 v154, v154
	v_exp_f32_e32 v155, v155
	v_exp_f32_e32 v159, v159
	v_add_f32_e32 v158, 1.0, v158
	v_add_f32_e32 v160, 1.0, v160
	v_add_f32_e32 v0, 1.0, v0
	v_add_f32_e32 v154, 1.0, v154
	v_add_f32_e32 v155, 1.0, v155
	v_rcp_f32_e32 v158, v158
	v_add_f32_e32 v159, 1.0, v159
	v_rcp_f32_e32 v160, v160
	v_rcp_f32_e32 v0, v0
	v_rcp_f32_e32 v154, v154
	v_rcp_f32_e32 v155, v155
	v_rcp_f32_e32 v159, v159
	s_mov_b32 s2, 0x17a08000
	v_cvt_pk_bf16_f32 v156, v156, v157
	v_cvt_pk_bf16_f32 v157, v158, v160
	v_add_co_u32_e32 v158, vcc, s2, v148
	v_cvt_pk_bf16_f32 v154, v0, v154
	v_cvt_pk_bf16_f32 v155, v155, v159
	v_addc_co_u32_e32 v159, vcc, 0, v149, vcc
	global_store_dwordx4 v[158:159], v[154:157], off
	v_fma_f32 v0, v86, v152, v134
	v_fma_f32 v158, v84, v152, v132
	v_fma_f32 v154, v82, v152, v130
	v_fma_f32 v155, v83, v152, v131
	v_mul_f32_e32 v154, 0xbfb8aa3b, v154
	v_mul_f32_e32 v155, 0xbfb8aa3b, v155
	v_exp_f32_e32 v154, v154
	v_exp_f32_e32 v155, v155
	v_fma_f32 v159, v89, v152, v137
	v_mul_f32_e32 v158, 0xbfb8aa3b, v158
	v_add_f32_e32 v154, 1.0, v154
	v_add_f32_e32 v155, 1.0, v155
	v_rcp_f32_e32 v156, v154
	v_fma_f32 v154, v87, v152, v135
	v_rcp_f32_e32 v157, v155
	v_fma_f32 v155, v88, v152, v136
	v_fma_f32 v152, v85, v152, v133
	v_mul_f32_e32 v152, 0xbfb8aa3b, v152
	v_mul_f32_e32 v0, 0xbfb8aa3b, v0
	v_mul_f32_e32 v154, 0xbfb8aa3b, v154
	v_mul_f32_e32 v155, 0xbfb8aa3b, v155
	v_exp_f32_e32 v158, v158
	v_mul_f32_e32 v159, 0xbfb8aa3b, v159
	v_exp_f32_e32 v152, v152
	v_exp_f32_e32 v0, v0
	v_exp_f32_e32 v154, v154
	v_exp_f32_e32 v155, v155
	v_exp_f32_e32 v159, v159
	v_add_f32_e32 v158, 1.0, v158
	v_add_f32_e32 v152, 1.0, v152
	v_add_f32_e32 v0, 1.0, v0
	v_add_f32_e32 v154, 1.0, v154
	v_add_f32_e32 v155, 1.0, v155
	v_rcp_f32_e32 v158, v158
	v_add_f32_e32 v159, 1.0, v159
	v_rcp_f32_e32 v152, v152
	v_rcp_f32_e32 v0, v0
	v_rcp_f32_e32 v154, v154
	v_rcp_f32_e32 v155, v155
	v_rcp_f32_e32 v159, v159
	s_mov_b32 s2, 0x17a0a000
	v_cvt_pk_bf16_f32 v156, v156, v157
	v_cvt_pk_bf16_f32 v157, v158, v152
	v_add_co_u32_e32 v158, vcc, s2, v148
	v_cvt_pk_bf16_f32 v154, v0, v154
	v_cvt_pk_bf16_f32 v155, v155, v159
	v_addc_co_u32_e32 v159, vcc, 0, v149, vcc
	global_store_dwordx4 v[158:159], v[154:157], off
	v_fma_f32 v152, v74, v153, v138
	v_mul_f32_e32 v152, 0xbfb8aa3b, v152
	v_fma_f32 v155, v75, v153, v139
	v_mul_f32_e32 v155, 0xbfb8aa3b, v155
	v_exp_f32_e32 v155, v155
	v_exp_f32_e32 v152, v152
	v_fma_f32 v158, v81, v153, v145
	v_fma_f32 v0, v78, v153, v142
	v_add_f32_e32 v155, 1.0, v155
	v_rcp_f32_e32 v156, v155
	v_fma_f32 v155, v80, v153, v144
	v_fma_f32 v154, v79, v153, v143
	v_mul_f32_e32 v155, 0xbfb8aa3b, v155
	v_fma_f32 v157, v76, v153, v140
	v_mul_f32_e32 v158, 0xbfb8aa3b, v158
	v_fma_f32 v159, v77, v153, v141
	v_mul_f32_e32 v0, 0xbfb8aa3b, v0
	v_add_f32_e32 v152, 1.0, v152
	v_mul_f32_e32 v154, 0xbfb8aa3b, v154
	v_exp_f32_e32 v155, v155
	v_mul_f32_e32 v157, 0xbfb8aa3b, v157
	v_exp_f32_e32 v158, v158
	v_mul_f32_e32 v159, 0xbfb8aa3b, v159
	v_exp_f32_e32 v0, v0
	v_rcp_f32_e32 v152, v152
	v_exp_f32_e32 v154, v154
	v_exp_f32_e32 v157, v157
	v_exp_f32_e32 v159, v159
	v_add_f32_e32 v155, 1.0, v155
; DI float sigmoidf_(float x) { return __builtin_amdgcn_rcpf(1.f + fast_exp(-x)); }
; #define PK8(v0, v1) ((u32x4){pk2((v0)[0], (v0)[1]), pk2((v0)[2], (v0)[3]), pk2((v1)[0], (v1)[1]), pk2((v1)[2], (v1)[3])})
;     DI void operator()(const f32x4 (&acc)[2][2][4][2], const Unit& u, int wr, int wc, int fr, int fq, int tid, LAS unsigned char* lds) const {
;     ...
; #pragma unroll
;             for (int ai = 0; ai < 2; ++ai)
; #pragma unroll
;                 for (int m = 0; m < 4; ++m)
; #pragma unroll
;                     for (int bj = 0; bj < 2; ++bj) { f32x4 g0, g1;
;                         const f32x4 a0 = acc[ai][bj][m][0] * rs[ai][m] + bv[bj][0], a1 = acc[ai][bj][m][1] * rs[ai][m] + bv[bj][1];
; #pragma unroll
;                         for (int e = 0; e < 4; ++e) { g0[e] = sigmoidf_(a0[e]); g1[e] = sigmoidf_(a1[e]); }
;                         st[((ai * 4 + m) * 2 + bj) * 512] = PK8(g0, g1); }
	v_add_f32_e32 v158, 1.0, v158
	v_add_f32_e32 v0, 1.0, v0
	v_add_f32_e32 v154, 1.0, v154
	v_rcp_f32_e32 v155, v155
	v_add_f32_e32 v157, 1.0, v157
	v_rcp_f32_e32 v158, v158
	v_add_f32_e32 v159, 1.0, v159
	v_cvt_pk_bf16_f32 v156, v152, v156
	v_fma_f32 v152, v66, v153, v130
	v_rcp_f32_e32 v0, v0
	v_rcp_f32_e32 v154, v154
	v_rcp_f32_e32 v157, v157
	v_rcp_f32_e32 v159, v159
	v_mul_f32_e32 v152, 0xbfb8aa3b, v152
	v_exp_f32_e32 v152, v152
	s_mov_b32 s2, 0x17a0c000
	v_cvt_pk_bf16_f32 v155, v155, v158
	v_add_co_u32_e32 v158, vcc, s2, v148
	v_cvt_pk_bf16_f32 v154, v0, v154
	v_cvt_pk_bf16_f32 v157, v157, v159
	v_addc_co_u32_e32 v159, vcc, 0, v149, vcc
	global_store_dwordx4 v[158:159], v[154:157], off
	v_add_f32_e32 v152, 1.0, v152
	v_fma_f32 v158, v73, v153, v137
	v_fma_f32 v156, v72, v153, v136
	v_fma_f32 v0, v70, v153, v134
	v_rcp_f32_e32 v154, v152
	v_fma_f32 v152, v71, v153, v135
	v_fma_f32 v155, v67, v153, v131
	v_mul_f32_e32 v156, 0xbfb8aa3b, v156
	v_fma_f32 v157, v68, v153, v132
	v_mul_f32_e32 v158, 0xbfb8aa3b, v158
	v_fma_f32 v153, v69, v153, v133
	v_mul_f32_e32 v0, 0xbfb8aa3b, v0
	v_mul_f32_e32 v152, 0xbfb8aa3b, v152
	v_mul_f32_e32 v155, 0xbfb8aa3b, v155
	v_exp_f32_e32 v156, v156
	v_mul_f32_e32 v157, 0xbfb8aa3b, v157
	v_exp_f32_e32 v158, v158
	v_mul_f32_e32 v153, 0xbfb8aa3b, v153
	v_exp_f32_e32 v0, v0
	v_exp_f32_e32 v152, v152
	v_exp_f32_e32 v155, v155
	v_exp_f32_e32 v157, v157
	v_exp_f32_e32 v153, v153
	v_add_f32_e32 v156, 1.0, v156
	v_add_f32_e32 v158, 1.0, v158
	v_add_f32_e32 v0, 1.0, v0
	v_add_f32_e32 v152, 1.0, v152
	v_add_f32_e32 v155, 1.0, v155
	v_rcp_f32_e32 v156, v156
	v_add_f32_e32 v157, 1.0, v157
	v_rcp_f32_e32 v158, v158
	v_add_f32_e32 v153, 1.0, v153
	v_rcp_f32_e32 v0, v0
	v_rcp_f32_e32 v152, v152
	v_rcp_f32_e32 v155, v155
	v_rcp_f32_e32 v157, v157
	v_rcp_f32_e32 v159, v153
	s_mov_b32 s2, 0x17a0e000
	v_cvt_pk_bf16_f32 v153, v156, v158
	v_add_co_u32_e32 v156, vcc, s2, v148
	v_cvt_pk_bf16_f32 v152, v0, v152
	v_cvt_pk_bf16_f32 v154, v154, v155
	v_cvt_pk_bf16_f32 v155, v157, v159
	v_addc_co_u32_e32 v157, vcc, 0, v149, vcc
	global_store_dwordx4 v[156:157], v[152:155], off
	s_waitcnt lgkmcnt(1)
	v_fma_f32 v156, v60, v150, v140
	v_fma_f32 v158, v61, v150, v141
	v_fma_f32 v152, v58, v150, v138
	v_fma_f32 v153, v59, v150, v139
	v_mul_f32_e32 v152, 0xbfb8aa3b, v152
	v_mul_f32_e32 v153, 0xbfb8aa3b, v153
	v_exp_f32_e32 v152, v152
	v_exp_f32_e32 v153, v153
	v_fma_f32 v0, v62, v150, v142
	v_mul_f32_e32 v156, 0xbfb8aa3b, v156
	v_add_f32_e32 v152, 1.0, v152
	v_add_f32_e32 v153, 1.0, v153
	v_rcp_f32_e32 v154, v152
	v_fma_f32 v152, v63, v150, v143
	v_rcp_f32_e32 v155, v153
	v_fma_f32 v153, v64, v150, v144
	v_fma_f32 v157, v65, v150, v145
	v_mul_f32_e32 v158, 0xbfb8aa3b, v158
	v_mul_f32_e32 v0, 0xbfb8aa3b, v0
	v_mul_f32_e32 v152, 0xbfb8aa3b, v152
	v_mul_f32_e32 v153, 0xbfb8aa3b, v153
	v_exp_f32_e32 v156, v156
	v_mul_f32_e32 v157, 0xbfb8aa3b, v157
	v_exp_f32_e32 v158, v158
	v_exp_f32_e32 v0, v0
	v_exp_f32_e32 v152, v152
	v_exp_f32_e32 v153, v153
	v_exp_f32_e32 v157, v157
	v_add_f32_e32 v156, 1.0, v156
	v_add_f32_e32 v158, 1.0, v158
	v_add_f32_e32 v0, 1.0, v0
	v_add_f32_e32 v152, 1.0, v152
	v_add_f32_e32 v153, 1.0, v153
	v_rcp_f32_e32 v156, v156
	v_add_f32_e32 v157, 1.0, v157
	v_rcp_f32_e32 v158, v158
	v_rcp_f32_e32 v0, v0
	v_rcp_f32_e32 v152, v152
	v_rcp_f32_e32 v153, v153
	v_rcp_f32_e32 v157, v157
	s_mov_b32 s2, 0x17a10000
	v_cvt_pk_bf16_f32 v154, v154, v155
	v_cvt_pk_bf16_f32 v155, v156, v158
	v_add_co_u32_e32 v156, vcc, s2, v148
	v_cvt_pk_bf16_f32 v152, v0, v152
	v_cvt_pk_bf16_f32 v153, v153, v157
	v_addc_co_u32_e32 v157, vcc, 0, v149, vcc
	global_store_dwordx4 v[156:157], v[152:155], off
	v_fma_f32 v0, v54, v150, v134
	v_fma_f32 v156, v52, v150, v132
	v_fma_f32 v152, v50, v150, v130
	v_fma_f32 v153, v51, v150, v131
	v_mul_f32_e32 v152, 0xbfb8aa3b, v152
	v_mul_f32_e32 v153, 0xbfb8aa3b, v153
	v_exp_f32_e32 v152, v152
	v_exp_f32_e32 v153, v153
	v_fma_f32 v157, v57, v150, v137
	v_mul_f32_e32 v156, 0xbfb8aa3b, v156
	v_add_f32_e32 v152, 1.0, v152
	v_add_f32_e32 v153, 1.0, v153
	v_rcp_f32_e32 v154, v152
	v_fma_f32 v152, v55, v150, v135
	v_rcp_f32_e32 v155, v153
	v_fma_f32 v153, v56, v150, v136
	v_fma_f32 v150, v53, v150, v133
	v_mul_f32_e32 v150, 0xbfb8aa3b, v150
	v_mul_f32_e32 v0, 0xbfb8aa3b, v0
	v_mul_f32_e32 v152, 0xbfb8aa3b, v152
	v_mul_f32_e32 v153, 0xbfb8aa3b, v153
	v_exp_f32_e32 v156, v156
	v_mul_f32_e32 v157, 0xbfb8aa3b, v157
	v_exp_f32_e32 v150, v150
	v_exp_f32_e32 v0, v0
	v_exp_f32_e32 v152, v152
	v_exp_f32_e32 v153, v153
	v_exp_f32_e32 v157, v157
	v_add_f32_e32 v156, 1.0, v156
	v_add_f32_e32 v150, 1.0, v150
	v_add_f32_e32 v0, 1.0, v0
	v_add_f32_e32 v152, 1.0, v152
	v_add_f32_e32 v153, 1.0, v153
	v_rcp_f32_e32 v156, v156
	v_add_f32_e32 v157, 1.0, v157
	v_rcp_f32_e32 v150, v150
	v_rcp_f32_e32 v0, v0
	v_rcp_f32_e32 v152, v152
	v_rcp_f32_e32 v153, v153
	v_rcp_f32_e32 v157, v157
	s_mov_b32 s2, 0x17a12000
	v_cvt_pk_bf16_f32 v154, v154, v155
	v_cvt_pk_bf16_f32 v155, v156, v150
	v_add_co_u32_e32 v156, vcc, s2, v148
	v_cvt_pk_bf16_f32 v152, v0, v152
	v_cvt_pk_bf16_f32 v153, v153, v157
	v_addc_co_u32_e32 v157, vcc, 0, v149, vcc
	global_store_dwordx4 v[156:157], v[152:155], off
	v_fma_f32 v150, v42, v151, v138
	v_mul_f32_e32 v150, 0xbfb8aa3b, v150
	v_fma_f32 v153, v43, v151, v139
	v_mul_f32_e32 v153, 0xbfb8aa3b, v153
	v_exp_f32_e32 v153, v153
	v_exp_f32_e32 v150, v150
	v_fma_f32 v156, v49, v151, v145
	v_fma_f32 v0, v46, v151, v142
	v_add_f32_e32 v153, 1.0, v153
	v_rcp_f32_e32 v154, v153
	v_fma_f32 v153, v48, v151, v144
	v_fma_f32 v152, v47, v151, v143
	v_mul_f32_e32 v153, 0xbfb8aa3b, v153
	v_fma_f32 v155, v44, v151, v140
	v_mul_f32_e32 v156, 0xbfb8aa3b, v156
; DI float sigmoidf_(float x) { return __builtin_amdgcn_rcpf(1.f + fast_exp(-x)); }
; #define PK8(v0, v1) ((u32x4){pk2((v0)[0], (v0)[1]), pk2((v0)[2], (v0)[3]), pk2((v1)[0], (v1)[1]), pk2((v1)[2], (v1)[3])})
;     DI void operator()(const f32x4 (&acc)[2][2][4][2], const Unit& u, int wr, int wc, int fr, int fq, int tid, LAS unsigned char* lds) const {
;     ...
; #pragma unroll
;             for (int ai = 0; ai < 2; ++ai)
; #pragma unroll
;                 for (int m = 0; m < 4; ++m)
; #pragma unroll
;                     for (int bj = 0; bj < 2; ++bj) { f32x4 g0, g1;
;                         const f32x4 a0 = acc[ai][bj][m][0] * rs[ai][m] + bv[bj][0], a1 = acc[ai][bj][m][1] * rs[ai][m] + bv[bj][1];
; #pragma unroll
;                         for (int e = 0; e < 4; ++e) { g0[e] = sigmoidf_(a0[e]); g1[e] = sigmoidf_(a1[e]); }
;                         st[((ai * 4 + m) * 2 + bj) * 512] = PK8(g0, g1); }
	v_fma_f32 v157, v45, v151, v141
	v_mul_f32_e32 v0, 0xbfb8aa3b, v0
	v_add_f32_e32 v150, 1.0, v150
	v_mul_f32_e32 v152, 0xbfb8aa3b, v152
	v_exp_f32_e32 v153, v153
	v_mul_f32_e32 v155, 0xbfb8aa3b, v155
	v_exp_f32_e32 v156, v156
	v_mul_f32_e32 v157, 0xbfb8aa3b, v157
	v_exp_f32_e32 v0, v0
	v_rcp_f32_e32 v150, v150
	v_exp_f32_e32 v152, v152
	v_exp_f32_e32 v155, v155
	v_exp_f32_e32 v157, v157
	v_add_f32_e32 v153, 1.0, v153
	v_add_f32_e32 v156, 1.0, v156
	v_add_f32_e32 v0, 1.0, v0
	v_add_f32_e32 v152, 1.0, v152
	v_rcp_f32_e32 v153, v153
	v_add_f32_e32 v155, 1.0, v155
	v_rcp_f32_e32 v156, v156
	v_add_f32_e32 v157, 1.0, v157
	v_cvt_pk_bf16_f32 v154, v150, v154
	v_fma_f32 v150, v34, v151, v130
	v_rcp_f32_e32 v0, v0
	v_rcp_f32_e32 v152, v152
	v_rcp_f32_e32 v155, v155
	v_rcp_f32_e32 v157, v157
	v_mul_f32_e32 v150, 0xbfb8aa3b, v150
	v_exp_f32_e32 v150, v150
	s_mov_b32 s2, 0x17a14000
	v_cvt_pk_bf16_f32 v153, v153, v156
	v_add_co_u32_e32 v156, vcc, s2, v148
	v_cvt_pk_bf16_f32 v152, v0, v152
	v_cvt_pk_bf16_f32 v155, v155, v157
	v_addc_co_u32_e32 v157, vcc, 0, v149, vcc
	global_store_dwordx4 v[156:157], v[152:155], off
	v_add_f32_e32 v150, 1.0, v150
	v_fma_f32 v156, v41, v151, v137
	v_fma_f32 v154, v40, v151, v136
	v_fma_f32 v0, v38, v151, v134
	v_rcp_f32_e32 v152, v150
	v_fma_f32 v150, v39, v151, v135
	v_fma_f32 v153, v35, v151, v131
	v_mul_f32_e32 v154, 0xbfb8aa3b, v154
	v_fma_f32 v155, v36, v151, v132
	v_mul_f32_e32 v156, 0xbfb8aa3b, v156
	v_fma_f32 v151, v37, v151, v133
	v_mul_f32_e32 v0, 0xbfb8aa3b, v0
	v_mul_f32_e32 v150, 0xbfb8aa3b, v150
	v_mul_f32_e32 v153, 0xbfb8aa3b, v153
	v_exp_f32_e32 v154, v154
	v_mul_f32_e32 v155, 0xbfb8aa3b, v155
	v_exp_f32_e32 v156, v156
	v_mul_f32_e32 v151, 0xbfb8aa3b, v151
	v_exp_f32_e32 v0, v0
	v_exp_f32_e32 v150, v150
	v_exp_f32_e32 v153, v153
	v_exp_f32_e32 v155, v155
	v_exp_f32_e32 v151, v151
	v_add_f32_e32 v154, 1.0, v154
	v_add_f32_e32 v156, 1.0, v156
	v_add_f32_e32 v0, 1.0, v0
	v_add_f32_e32 v150, 1.0, v150
	v_add_f32_e32 v153, 1.0, v153
	v_rcp_f32_e32 v154, v154
	v_add_f32_e32 v155, 1.0, v155
	v_rcp_f32_e32 v156, v156
	v_add_f32_e32 v151, 1.0, v151
	v_rcp_f32_e32 v0, v0
	v_rcp_f32_e32 v150, v150
	v_rcp_f32_e32 v153, v153
	v_rcp_f32_e32 v155, v155
	v_rcp_f32_e32 v157, v151
	s_mov_b32 s2, 0x17a16000
	v_cvt_pk_bf16_f32 v151, v154, v156
	v_add_co_u32_e32 v154, vcc, s2, v148
	v_cvt_pk_bf16_f32 v150, v0, v150
	v_cvt_pk_bf16_f32 v152, v152, v153
	v_cvt_pk_bf16_f32 v153, v155, v157
	v_addc_co_u32_e32 v155, vcc, 0, v149, vcc
	global_store_dwordx4 v[154:155], v[150:153], off
	s_waitcnt lgkmcnt(0)
; DI float sigmoidf_(float x) { return __builtin_amdgcn_rcpf(1.f + fast_exp(-x)); }
; #define PK8(v0, v1) ((u32x4){pk2((v0)[0], (v0)[1]), pk2((v0)[2], (v0)[3]), pk2((v1)[0], (v1)[1]), pk2((v1)[2], (v1)[3])})
;     DI void operator()(const f32x4 (&acc)[2][2][4][2], const Unit& u, int wr, int wc, int fr, int fq, int tid, LAS unsigned char* lds) const {
;     ...
; #pragma unroll
;             for (int ai = 0; ai < 2; ++ai)
; #pragma unroll
;                 for (int m = 0; m < 4; ++m)
; #pragma unroll
;                     for (int bj = 0; bj < 2; ++bj) { f32x4 g0, g1;
;                         const f32x4 a0 = acc[ai][bj][m][0] * rs[ai][m] + bv[bj][0], a1 = acc[ai][bj][m][1] * rs[ai][m] + bv[bj][1];
; #pragma unroll
;                         for (int e = 0; e < 4; ++e) { g0[e] = sigmoidf_(a0[e]); g1[e] = sigmoidf_(a1[e]); }
;                         st[((ai * 4 + m) * 2 + bj) * 512] = PK8(g0, g1); }
	v_fma_f32 v154, v28, v146, v140
	v_fma_f32 v156, v29, v146, v141
	v_fma_f32 v150, v26, v146, v138
	v_fma_f32 v151, v27, v146, v139
	v_mul_f32_e32 v150, 0xbfb8aa3b, v150
	v_mul_f32_e32 v151, 0xbfb8aa3b, v151
	v_exp_f32_e32 v150, v150
	v_exp_f32_e32 v151, v151
	v_fma_f32 v0, v30, v146, v142
	v_mul_f32_e32 v154, 0xbfb8aa3b, v154
	v_add_f32_e32 v150, 1.0, v150
	v_add_f32_e32 v151, 1.0, v151
	v_rcp_f32_e32 v152, v150
	v_fma_f32 v150, v31, v146, v143
	v_rcp_f32_e32 v153, v151
	v_fma_f32 v151, v32, v146, v144
	v_fma_f32 v155, v33, v146, v145
	v_mul_f32_e32 v156, 0xbfb8aa3b, v156
	v_mul_f32_e32 v0, 0xbfb8aa3b, v0
	v_mul_f32_e32 v150, 0xbfb8aa3b, v150
	v_mul_f32_e32 v151, 0xbfb8aa3b, v151
	v_exp_f32_e32 v154, v154
	v_mul_f32_e32 v155, 0xbfb8aa3b, v155
	v_exp_f32_e32 v156, v156
	v_exp_f32_e32 v0, v0
	v_exp_f32_e32 v150, v150
	v_exp_f32_e32 v151, v151
	v_exp_f32_e32 v155, v155
	v_add_f32_e32 v154, 1.0, v154
	v_add_f32_e32 v156, 1.0, v156
	v_add_f32_e32 v0, 1.0, v0
	v_add_f32_e32 v150, 1.0, v150
	v_add_f32_e32 v151, 1.0, v151
	v_rcp_f32_e32 v154, v154
	v_add_f32_e32 v155, 1.0, v155
	v_rcp_f32_e32 v156, v156
	v_rcp_f32_e32 v0, v0
	v_rcp_f32_e32 v150, v150
	v_rcp_f32_e32 v151, v151
	v_rcp_f32_e32 v155, v155
	s_mov_b32 s2, 0x17a18000
	v_cvt_pk_bf16_f32 v152, v152, v153
	v_cvt_pk_bf16_f32 v153, v154, v156
	v_add_co_u32_e32 v154, vcc, s2, v148
	v_cvt_pk_bf16_f32 v150, v0, v150
	v_cvt_pk_bf16_f32 v151, v151, v155
	v_addc_co_u32_e32 v155, vcc, 0, v149, vcc
	global_store_dwordx4 v[154:155], v[150:153], off
	v_fma_f32 v0, v22, v146, v134
	v_mul_f32_e32 v0, 0xbfb8aa3b, v0
	v_fma_f32 v150, v18, v146, v130
	v_mul_f32_e32 v150, 0xbfb8aa3b, v150
	v_exp_f32_e32 v150, v150
	v_exp_f32_e32 v0, v0
	v_fma_f32 v138, v10, v147, v138
	v_mul_f32_e32 v138, 0xbfb8aa3b, v138
	v_add_f32_e32 v150, 1.0, v150
	v_rcp_f32_e32 v152, v150
	v_fma_f32 v150, v23, v146, v135
	v_mul_f32_e32 v150, 0xbfb8aa3b, v150
	v_exp_f32_e32 v150, v150
	v_add_f32_e32 v0, 1.0, v0
	v_exp_f32_e32 v138, v138
	v_rcp_f32_e32 v0, v0
	v_add_f32_e32 v150, 1.0, v150
	v_rcp_f32_e32 v150, v150
	v_add_f32_e32 v138, 1.0, v138
	v_fma_f32 v151, v19, v146, v131
	v_mul_f32_e32 v151, 0xbfb8aa3b, v151
	v_cvt_pk_bf16_f32 v150, v0, v150
	v_fma_f32 v0, v14, v147, v142
	v_rcp_f32_e32 v142, v138
	v_fma_f32 v138, v15, v147, v143
	v_mul_f32_e32 v0, 0xbfb8aa3b, v0
	v_mul_f32_e32 v138, 0xbfb8aa3b, v138
	v_exp_f32_e32 v151, v151
	v_exp_f32_e32 v0, v0
	v_exp_f32_e32 v138, v138
	v_fma_f32 v139, v11, v147, v139
	v_mul_f32_e32 v139, 0xbfb8aa3b, v139
	v_fma_f32 v140, v12, v147, v140
	v_exp_f32_e32 v139, v139
	v_mul_f32_e32 v140, 0xbfb8aa3b, v140
	v_fma_f32 v130, v2, v147, v130
	v_fma_f32 v131, v3, v147, v131
	v_fma_f32 v154, v20, v146, v132
	v_exp_f32_e32 v140, v140
	v_mul_f32_e32 v130, 0xbfb8aa3b, v130
	v_mul_f32_e32 v131, 0xbfb8aa3b, v131
	v_fma_f32 v132, v4, v147, v132
	v_add_f32_e32 v151, 1.0, v151
	v_add_f32_e32 v0, 1.0, v0
	v_add_f32_e32 v138, 1.0, v138
	v_exp_f32_e32 v130, v130
	v_exp_f32_e32 v131, v131
	v_mul_f32_e32 v132, 0xbfb8aa3b, v132
	v_rcp_f32_e32 v153, v151
	v_fma_f32 v151, v24, v146, v136
	v_fma_f32 v155, v25, v146, v137
	v_fma_f32 v146, v21, v146, v133
	v_rcp_f32_e32 v0, v0
	v_rcp_f32_e32 v138, v138
	v_exp_f32_e32 v132, v132
	v_mul_f32_e32 v154, 0xbfb8aa3b, v154
	v_mul_f32_e32 v146, 0xbfb8aa3b, v146
	v_add_f32_e32 v139, 1.0, v139
	v_mul_f32_e32 v151, 0xbfb8aa3b, v151
	v_exp_f32_e32 v154, v154
	v_mul_f32_e32 v155, 0xbfb8aa3b, v155
	v_exp_f32_e32 v146, v146
	v_rcp_f32_e32 v143, v139
	v_fma_f32 v139, v16, v147, v144
	v_add_f32_e32 v140, 1.0, v140
	v_fmac_f32_e32 v145, v17, v147
	v_exp_f32_e32 v151, v151
	v_exp_f32_e32 v155, v155
	v_mul_f32_e32 v139, 0xbfb8aa3b, v139
	v_rcp_f32_e32 v144, v140
	v_mul_f32_e32 v140, 0xbfb8aa3b, v145
	v_add_f32_e32 v130, 1.0, v130
	v_add_f32_e32 v131, 1.0, v131
	v_exp_f32_e32 v139, v139
	v_exp_f32_e32 v140, v140
	v_cvt_pk_bf16_f32 v138, v0, v138
	v_fma_f32 v0, v6, v147, v134
	v_rcp_f32_e32 v134, v130
	v_fma_f32 v130, v7, v147, v135
	v_rcp_f32_e32 v135, v131
	v_fma_f32 v131, v8, v147, v136
	v_add_f32_e32 v132, 1.0, v132
	v_fmac_f32_e32 v137, v9, v147
	v_fmac_f32_e32 v141, v13, v147
	v_mul_f32_e32 v131, 0xbfb8aa3b, v131
	v_rcp_f32_e32 v136, v132
	v_mul_f32_e32 v132, 0xbfb8aa3b, v137
	v_fmac_f32_e32 v133, v5, v147
	v_add_f32_e32 v154, 1.0, v154
	v_add_f32_e32 v146, 1.0, v146
	v_mul_f32_e32 v141, 0xbfb8aa3b, v141
	v_mul_f32_e32 v0, 0xbfb8aa3b, v0
	v_mul_f32_e32 v130, 0xbfb8aa3b, v130
	v_exp_f32_e32 v131, v131
	v_exp_f32_e32 v132, v132
	v_mul_f32_e32 v133, 0xbfb8aa3b, v133
	v_add_f32_e32 v151, 1.0, v151
	v_rcp_f32_e32 v154, v154
	v_add_f32_e32 v155, 1.0, v155
	v_rcp_f32_e32 v146, v146
	v_exp_f32_e32 v141, v141
	v_exp_f32_e32 v0, v0
	v_exp_f32_e32 v130, v130
	v_exp_f32_e32 v133, v133
	v_rcp_f32_e32 v151, v151
	v_rcp_f32_e32 v155, v155
	v_add_f32_e32 v139, 1.0, v139
	v_add_f32_e32 v140, 1.0, v140
	v_rcp_f32_e32 v139, v139
	v_rcp_f32_e32 v140, v140
	s_mov_b32 s2, 0x17a1a000
	v_add_f32_e32 v131, 1.0, v131
	v_add_f32_e32 v132, 1.0, v132
	v_cvt_pk_bf16_f32 v152, v152, v153
	v_cvt_pk_bf16_f32 v153, v154, v146
	v_add_co_u32_e32 v154, vcc, s2, v148
	v_add_f32_e32 v141, 1.0, v141
	v_add_f32_e32 v0, 1.0, v0
	v_add_f32_e32 v130, 1.0, v130
	v_rcp_f32_e32 v131, v131
	v_rcp_f32_e32 v132, v132
	v_add_f32_e32 v133, 1.0, v133
	v_cvt_pk_bf16_f32 v151, v151, v155
	v_addc_co_u32_e32 v155, vcc, 0, v149, vcc
	v_rcp_f32_e32 v141, v141
	s_mov_b32 s2, 0x17a1c000
	v_rcp_f32_e32 v0, v0
	v_rcp_f32_e32 v130, v130
	v_rcp_f32_e32 v133, v133
	v_cvt_pk_bf16_f32 v139, v139, v140
	v_cvt_pk_bf16_f32 v140, v142, v143
	v_add_co_u32_e32 v142, vcc, s2, v148
	v_cvt_pk_bf16_f32 v131, v131, v132
	s_nop 0
	v_addc_co_u32_e32 v143, vcc, 0, v149, vcc
	v_cvt_pk_bf16_f32 v132, v134, v135
	v_add_co_u32_e32 v134, vcc, 0x17a1e000, v148
	v_cvt_pk_bf16_f32 v141, v144, v141
	v_cvt_pk_bf16_f32 v130, v0, v130
	v_cvt_pk_bf16_f32 v133, v136, v133
	v_addc_co_u32_e32 v135, vcc, 0, v149, vcc
	global_store_dwordx4 v[154:155], v[150:153], off
	global_store_dwordx4 v[142:143], v[138:141], off
	global_store_dwordx4 v[134:135], v[130:133], off
